# speedup vs baseline: 1.0037x; 1.0037x over previous
.LBB0_42:
	s_bitcmp0_b32 s75, 2
	ds_write2_b32 v2, v38, v39 offset0:140 offset1:206
	s_cselect_b32 s3, s69, s71
	s_cselect_b32 s10, s68, s92
	s_lshl_b32 s2, s2, 4
	s_add_i32 s11, s26, 0xfffffc00
	s_waitcnt lgkmcnt(0)
	s_and_b32 s2, s2, 0x380
	s_and_b32 s11, s11, 0x60
	s_lshl_b64 s[0:1], s[72:73], 1
	s_or_b32 s2, s2, s11
	s_waitcnt vmcnt(0)
	ds_read2_b32 v[36:37], v75 offset1:33
	s_add_u32 s0, s10, s0
	s_waitcnt lgkmcnt(0)
	v_cvt_pk_bf16_f32 v36, v36, v37
	ds_read2_b32 v[38:39], v75 offset0:66 offset1:99
	v_mov_b32_e32 v33, v3
	s_addc_u32 s1, s3, s1
	v_or_b32_e32 v2, s2, v74
	s_waitcnt lgkmcnt(0)
	v_cvt_pk_bf16_f32 v37, v38, v39
	ds_read2_b32 v[38:39], v75 offset0:132 offset1:165
	v_lshl_add_u64 v[42:43], s[0:1], 0, v[32:33]
	v_lshlrev_b32_e32 v2, 9, v2
	s_waitcnt lgkmcnt(0)
	v_cvt_pk_bf16_f32 v38, v38, v39
	ds_read2_b32 v[40:41], v75 offset0:198 offset1:231
	s_waitcnt lgkmcnt(0)
	v_cvt_pk_bf16_f32 v39, v40, v41
	v_lshl_add_u64 v[44:45], v[42:43], 0, v[2:3]
	ds_read2_b32 v[40:41], v75 offset0:8 offset1:41
	global_store_dwordx4 v[44:45], v[36:39], off sc1
	v_or_b32_e32 v2, s2, v76
	v_lshlrev_b32_e32 v2, 9, v2
	s_waitcnt lgkmcnt(0)
	v_cvt_pk_bf16_f32 v36, v40, v41
	ds_read2_b32 v[38:39], v75 offset0:74 offset1:107
	s_waitcnt lgkmcnt(0)
	v_cvt_pk_bf16_f32 v37, v38, v39
	ds_read2_b32 v[38:39], v75 offset0:140 offset1:173
	s_waitcnt lgkmcnt(0)
	v_cvt_pk_bf16_f32 v38, v38, v39
	ds_read2_b32 v[40:41], v75 offset0:206 offset1:239
	s_waitcnt lgkmcnt(0)
	v_cvt_pk_bf16_f32 v39, v40, v41
	v_lshl_add_u64 v[44:45], v[42:43], 0, v[2:3]
	ds_read2_b32 v[40:41], v75 offset0:16 offset1:49
	global_store_dwordx4 v[44:45], v[36:39], off sc1
	v_or_b32_e32 v2, s2, v77
	v_lshlrev_b32_e32 v2, 9, v2
	s_waitcnt lgkmcnt(0)
	v_cvt_pk_bf16_f32 v36, v40, v41
	ds_read2_b32 v[38:39], v75 offset0:82 offset1:115
	s_waitcnt lgkmcnt(0)
	v_cvt_pk_bf16_f32 v37, v38, v39
	ds_read2_b32 v[38:39], v75 offset0:148 offset1:181
	s_waitcnt lgkmcnt(0)
	v_cvt_pk_bf16_f32 v38, v38, v39
	ds_read2_b32 v[40:41], v75 offset0:214 offset1:247
	s_waitcnt lgkmcnt(0)
	v_cvt_pk_bf16_f32 v39, v40, v41
	v_lshl_add_u64 v[44:45], v[42:43], 0, v[2:3]
	ds_read2_b32 v[40:41], v75 offset0:24 offset1:57
	global_store_dwordx4 v[44:45], v[36:39], off sc1
	v_or_b32_e32 v2, s2, v78
	v_lshlrev_b32_e32 v2, 9, v2
	s_waitcnt lgkmcnt(0)
	v_cvt_pk_bf16_f32 v36, v40, v41
	ds_read2_b32 v[38:39], v75 offset0:90 offset1:123
	s_waitcnt lgkmcnt(0)
	v_cvt_pk_bf16_f32 v37, v38, v39
	ds_read2_b32 v[38:39], v75 offset0:156 offset1:189
	s_waitcnt lgkmcnt(0)
	v_cvt_pk_bf16_f32 v38, v38, v39
	ds_read2_b32 v[40:41], v75 offset0:222 offset1:255
	s_waitcnt lgkmcnt(0)
	v_cvt_pk_bf16_f32 v39, v40, v41
	v_lshl_add_u64 v[40:41], v[42:43], 0, v[2:3]
	global_store_dwordx4 v[40:41], v[36:39], off sc1
	s_waitcnt lgkmcnt(0)
	s_mov_b64 s[0:1], 0
.LBB0_43:
	s_and_b64 vcc, exec, s[0:1]
	s_cbranch_vccz .LBB0_45
	s_and_b32 s0, s75, 0x7fc0
	s_addk_i32 s0, 0xb100
	s_add_i32 s1, s26, 0xfffffc00
	s_and_b32 s2, s1, 0x7e0
	v_or_b32_e32 v2, s0, v56
	s_lshl_b32 s72, s2, 2
	v_or_b32_e32 v40, 2, v2
	v_mov_b32_e32 v41, v3
	v_or_b32_e32 v42, 4, v2
	v_mov_b32_e32 v43, v3
	v_or_b32_e32 v44, 6, v2
	v_mov_b32_e32 v45, v3
	v_or_b32_e32 v46, 8, v2
	v_mov_b32_e32 v47, v3
	v_or_b32_e32 v48, 10, v2
	v_mov_b32_e32 v49, v3
	v_or_b32_e32 v50, 12, v2
	v_mov_b32_e32 v51, v3
	v_lshl_add_u64 v[36:37], v[6:7], 0, s[72:73]
	v_lshlrev_b64 v[38:39], 13, v[2:3]
	v_lshlrev_b64 v[40:41], 13, v[40:41]
	v_lshlrev_b64 v[42:43], 13, v[42:43]
	v_lshlrev_b64 v[44:45], 13, v[44:45]
	v_lshlrev_b64 v[46:47], 13, v[46:47]
	v_lshlrev_b64 v[48:49], 13, v[48:49]
	v_lshlrev_b64 v[50:51], 13, v[50:51]
	v_or_b32_e32 v52, 14, v2
	v_mov_b32_e32 v53, v3
	v_lshl_add_u64 v[38:39], v[36:37], 0, v[38:39]
	v_lshl_add_u64 v[40:41], v[36:37], 0, v[40:41]
	v_lshl_add_u64 v[42:43], v[36:37], 0, v[42:43]
	v_lshl_add_u64 v[44:45], v[36:37], 0, v[44:45]
	v_lshl_add_u64 v[46:47], v[36:37], 0, v[46:47]
	v_lshl_add_u64 v[48:49], v[36:37], 0, v[48:49]
	v_lshl_add_u64 v[50:51], v[36:37], 0, v[50:51]
	v_lshlrev_b64 v[52:53], 13, v[52:53]
	v_lshl_add_u64 v[52:53], v[36:37], 0, v[52:53]
	global_load_dword v33, v[38:39], off
	global_load_dword v35, v[40:41], off
	global_load_dword v54, v[42:43], off
	global_load_dword v55, v[44:45], off
	global_load_dword v79, v[46:47], off
	global_load_dword v80, v[48:49], off
	global_load_dword v81, v[50:51], off
	global_load_dword v82, v[52:53], off
	v_or_b32_e32 v38, 16, v2
	v_mov_b32_e32 v39, v3
	v_or_b32_e32 v40, 18, v2
	v_mov_b32_e32 v41, v3
	v_or_b32_e32 v42, 20, v2
	v_mov_b32_e32 v43, v3
	v_or_b32_e32 v44, 22, v2
	v_mov_b32_e32 v45, v3
	v_or_b32_e32 v46, 24, v2
	v_mov_b32_e32 v47, v3
	v_or_b32_e32 v48, 26, v2
	v_mov_b32_e32 v49, v3
	v_or_b32_e32 v50, 28, v2
	v_mov_b32_e32 v51, v3
	v_lshlrev_b64 v[38:39], 13, v[38:39]
	v_lshlrev_b64 v[40:41], 13, v[40:41]
	v_lshlrev_b64 v[42:43], 13, v[42:43]
	v_lshlrev_b64 v[44:45], 13, v[44:45]
	v_lshlrev_b64 v[46:47], 13, v[46:47]
	v_lshlrev_b64 v[48:49], 13, v[48:49]
	v_lshlrev_b64 v[50:51], 13, v[50:51]
	v_or_b32_e32 v52, 30, v2
	v_mov_b32_e32 v53, v3
	v_lshl_add_u64 v[38:39], v[36:37], 0, v[38:39]
	v_lshl_add_u64 v[40:41], v[36:37], 0, v[40:41]
	v_lshl_add_u64 v[42:43], v[36:37], 0, v[42:43]
	v_lshl_add_u64 v[44:45], v[36:37], 0, v[44:45]
	v_lshl_add_u64 v[46:47], v[36:37], 0, v[46:47]
	v_lshl_add_u64 v[48:49], v[36:37], 0, v[48:49]
	v_lshl_add_u64 v[50:51], v[36:37], 0, v[50:51]
	v_lshlrev_b64 v[52:53], 13, v[52:53]
	v_lshl_add_u64 v[52:53], v[36:37], 0, v[52:53]
	global_load_dword v83, v[38:39], off
	global_load_dword v84, v[40:41], off
	global_load_dword v85, v[42:43], off
	global_load_dword v86, v[44:45], off
	global_load_dword v87, v[46:47], off
	global_load_dword v88, v[48:49], off
	global_load_dword v89, v[50:51], off
	global_load_dword v90, v[52:53], off
	v_or_b32_e32 v38, 32, v2
	v_mov_b32_e32 v39, v3
	v_or_b32_e32 v40, 34, v2
	v_mov_b32_e32 v41, v3
	v_or_b32_e32 v42, 36, v2
	v_mov_b32_e32 v43, v3
	v_or_b32_e32 v44, 38, v2
	v_mov_b32_e32 v45, v3
	v_or_b32_e32 v46, 40, v2
	v_mov_b32_e32 v47, v3
	v_or_b32_e32 v48, 42, v2
	v_mov_b32_e32 v49, v3
	v_or_b32_e32 v50, 44, v2
	v_mov_b32_e32 v51, v3
	v_lshlrev_b64 v[38:39], 13, v[38:39]
	v_lshlrev_b64 v[40:41], 13, v[40:41]
	v_lshlrev_b64 v[42:43], 13, v[42:43]
	v_lshlrev_b64 v[44:45], 13, v[44:45]
	v_lshlrev_b64 v[46:47], 13, v[46:47]
	v_lshlrev_b64 v[48:49], 13, v[48:49]
	v_lshlrev_b64 v[50:51], 13, v[50:51]
	v_or_b32_e32 v52, 46, v2
	v_mov_b32_e32 v53, v3
	v_lshl_add_u64 v[38:39], v[36:37], 0, v[38:39]
	v_lshl_add_u64 v[40:41], v[36:37], 0, v[40:41]
	v_lshl_add_u64 v[42:43], v[36:37], 0, v[42:43]
	v_lshl_add_u64 v[44:45], v[36:37], 0, v[44:45]
	v_lshl_add_u64 v[46:47], v[36:37], 0, v[46:47]
	v_lshl_add_u64 v[48:49], v[36:37], 0, v[48:49]
	v_lshl_add_u64 v[50:51], v[36:37], 0, v[50:51]
	v_lshlrev_b64 v[52:53], 13, v[52:53]
	v_lshl_add_u64 v[52:53], v[36:37], 0, v[52:53]
	global_load_dword v91, v[38:39], off
	global_load_dword v92, v[40:41], off
	global_load_dword v93, v[42:43], off
	global_load_dword v94, v[44:45], off
	global_load_dword v95, v[46:47], off
	global_load_dword v96, v[48:49], off
	global_load_dword v97, v[50:51], off
	global_load_dword v98, v[52:53], off
	v_or_b32_e32 v38, 48, v2
	v_mov_b32_e32 v39, v3
	v_or_b32_e32 v40, 50, v2
	v_mov_b32_e32 v41, v3
	v_or_b32_e32 v42, 52, v2
	v_mov_b32_e32 v43, v3
	v_or_b32_e32 v44, 54, v2
	v_mov_b32_e32 v45, v3
	v_or_b32_e32 v46, 56, v2
	v_mov_b32_e32 v47, v3
	v_or_b32_e32 v48, 58, v2
	v_mov_b32_e32 v49, v3
	v_or_b32_e32 v50, 60, v2
	v_mov_b32_e32 v51, v3
	v_or_b32_e32 v2, 62, v2
	v_lshlrev_b64 v[38:39], 13, v[38:39]
	v_lshlrev_b64 v[40:41], 13, v[40:41]
	v_lshlrev_b64 v[42:43], 13, v[42:43]
	v_lshlrev_b64 v[44:45], 13, v[44:45]
	v_lshlrev_b64 v[46:47], 13, v[46:47]
	v_lshlrev_b64 v[48:49], 13, v[48:49]
	v_lshlrev_b64 v[50:51], 13, v[50:51]
	v_lshlrev_b64 v[52:53], 13, v[2:3]
	v_lshl_add_u64 v[38:39], v[36:37], 0, v[38:39]
	v_lshl_add_u64 v[40:41], v[36:37], 0, v[40:41]
	v_lshl_add_u64 v[42:43], v[36:37], 0, v[42:43]
	v_lshl_add_u64 v[44:45], v[36:37], 0, v[44:45]
	v_lshl_add_u64 v[46:47], v[36:37], 0, v[46:47]
	v_lshl_add_u64 v[48:49], v[36:37], 0, v[48:49]
	v_lshl_add_u64 v[50:51], v[36:37], 0, v[50:51]
	v_lshl_add_u64 v[36:37], v[36:37], 0, v[52:53]
	global_load_dword v2, v[38:39], off
	s_nop 0
	global_load_dword v38, v[40:41], off
	global_load_dword v39, v[42:43], off
	s_nop 0
	global_load_dword v40, v[44:45], off
	global_load_dword v41, v[46:47], off
	global_load_dword v42, v[48:49], off
	global_load_dword v43, v[50:51], off
	s_nop 0
	global_load_dword v36, v[36:37], off
	s_waitcnt vmcnt(30)
	ds_write2_b32 v58, v33, v35 offset1:66
	s_waitcnt vmcnt(28)
	ds_write2_b32 v58, v54, v55 offset0:132 offset1:198
	v_add_u32_e32 v33, 0x400, v58
	s_waitcnt vmcnt(26)
	ds_write2_b32 v33, v79, v80 offset0:8 offset1:74
	s_waitcnt vmcnt(24)
	ds_write2_b32 v33, v81, v82 offset0:140 offset1:206
	v_add_u32_e32 v33, 0x800, v58
	s_waitcnt vmcnt(22)
	ds_write2_b32 v33, v83, v84 offset0:16 offset1:82
	s_waitcnt vmcnt(20)
	ds_write2_b32 v33, v85, v86 offset0:148 offset1:214
	v_add_u32_e32 v33, 0xc00, v58
	s_waitcnt vmcnt(18)
	ds_write2_b32 v33, v87, v88 offset0:24 offset1:90
	s_waitcnt vmcnt(16)
	ds_write2_b32 v33, v89, v90 offset0:156 offset1:222
	v_add_u32_e32 v33, 0x1000, v58
	s_waitcnt vmcnt(14)
	ds_write2_b32 v33, v91, v92 offset0:32 offset1:98
	s_waitcnt vmcnt(12)
	ds_write2_b32 v33, v93, v94 offset0:164 offset1:230
	v_add_u32_e32 v33, 0x1400, v58
	s_waitcnt vmcnt(10)
	ds_write2_b32 v33, v95, v96 offset0:40 offset1:106
	s_waitcnt vmcnt(8)
	ds_write2_b32 v33, v97, v98 offset0:172 offset1:238
	v_add_u32_e32 v33, 0x1800, v58
	s_waitcnt vmcnt(6)
	ds_write2_b32 v33, v2, v38 offset0:48 offset1:114
	s_waitcnt vmcnt(4)
	ds_write2_b32 v33, v39, v40 offset0:180 offset1:246
	v_add_u32_e32 v2, 0x1c00, v58
	s_waitcnt vmcnt(2)
	ds_write2_b32 v2, v41, v42 offset0:56 offset1:122
	s_waitcnt vmcnt(0)
	ds_write2_b32 v2, v43, v36 offset0:188 offset1:254
	s_waitcnt lgkmcnt(0)
	ds_read2_b32 v[36:37], v75 offset1:33
	s_waitcnt lgkmcnt(0)
	v_cvt_pk_bf16_f32 v36, v36, v37
	ds_read2_b32 v[38:39], v75 offset0:66 offset1:99
	s_mov_b32 s1, s73
	v_or_b32_e32 v2, s2, v74
	s_waitcnt lgkmcnt(0)
	v_cvt_pk_bf16_f32 v37, v38, v39
	ds_read2_b32 v[38:39], v75 offset0:132 offset1:165
	v_lshl_add_u64 v[42:43], s[0:1], 1, v[8:9]
	v_lshlrev_b32_e32 v2, 14, v2
	s_waitcnt lgkmcnt(0)
	v_cvt_pk_bf16_f32 v38, v38, v39
	ds_read2_b32 v[40:41], v75 offset0:198 offset1:231
	s_waitcnt lgkmcnt(0)
	v_cvt_pk_bf16_f32 v39, v40, v41
	v_lshl_add_u64 v[44:45], v[42:43], 0, v[2:3]
	ds_read2_b32 v[40:41], v75 offset0:8 offset1:41
	global_store_dwordx4 v[44:45], v[36:39], off sc1
	v_or_b32_e32 v2, s2, v76
	v_lshlrev_b32_e32 v2, 14, v2
	s_waitcnt lgkmcnt(0)
	v_cvt_pk_bf16_f32 v36, v40, v41
	ds_read2_b32 v[38:39], v75 offset0:74 offset1:107
	s_waitcnt lgkmcnt(0)
	v_cvt_pk_bf16_f32 v37, v38, v39
	ds_read2_b32 v[38:39], v75 offset0:140 offset1:173
	s_waitcnt lgkmcnt(0)
	v_cvt_pk_bf16_f32 v38, v38, v39
	ds_read2_b32 v[40:41], v75 offset0:206 offset1:239
	s_waitcnt lgkmcnt(0)
	v_cvt_pk_bf16_f32 v39, v40, v41
	v_lshl_add_u64 v[44:45], v[42:43], 0, v[2:3]
	ds_read2_b32 v[40:41], v75 offset0:16 offset1:49
	global_store_dwordx4 v[44:45], v[36:39], off sc1
	v_or_b32_e32 v2, s2, v77
	v_lshlrev_b32_e32 v2, 14, v2
	s_waitcnt lgkmcnt(0)
	v_cvt_pk_bf16_f32 v36, v40, v41
	ds_read2_b32 v[38:39], v75 offset0:82 offset1:115
	s_waitcnt lgkmcnt(0)
	v_cvt_pk_bf16_f32 v37, v38, v39
	ds_read2_b32 v[38:39], v75 offset0:148 offset1:181
	s_waitcnt lgkmcnt(0)
	v_cvt_pk_bf16_f32 v38, v38, v39
	ds_read2_b32 v[40:41], v75 offset0:214 offset1:247
	s_waitcnt lgkmcnt(0)
	v_cvt_pk_bf16_f32 v39, v40, v41
	v_lshl_add_u64 v[44:45], v[42:43], 0, v[2:3]
	ds_read2_b32 v[40:41], v75 offset0:24 offset1:57
	global_store_dwordx4 v[44:45], v[36:39], off sc1
	v_or_b32_e32 v2, s2, v78
	v_lshlrev_b32_e32 v2, 14, v2
	s_waitcnt lgkmcnt(0)
	v_cvt_pk_bf16_f32 v36, v40, v41
	ds_read2_b32 v[38:39], v75 offset0:90 offset1:123
	s_waitcnt lgkmcnt(0)
	v_cvt_pk_bf16_f32 v37, v38, v39
	ds_read2_b32 v[38:39], v75 offset0:156 offset1:189
	s_waitcnt lgkmcnt(0)
	v_cvt_pk_bf16_f32 v38, v38, v39
	ds_read2_b32 v[40:41], v75 offset0:222 offset1:255
	s_waitcnt lgkmcnt(0)
	v_cvt_pk_bf16_f32 v39, v40, v41
	v_lshl_add_u64 v[40:41], v[42:43], 0, v[2:3]
	global_store_dwordx4 v[40:41], v[36:39], off sc1
	s_waitcnt lgkmcnt(0)

.LBB0_71:
	ds_write2_b32 v2, v38, v39 offset0:140 offset1:206
	s_waitcnt lgkmcnt(0)
	s_waitcnt vmcnt(0)
	ds_read2_b32 v[36:37], v75 offset1:33
	s_waitcnt lgkmcnt(0)
	v_cvt_pk_bf16_f32 v36, v36, v37
	ds_read2_b32 v[38:39], v75 offset0:66 offset1:99
	s_lshl_b32 s72, s3, 1
	v_or_b32_e32 v2, s2, v74
	s_waitcnt lgkmcnt(0)
	v_cvt_pk_bf16_f32 v37, v38, v39
	ds_read2_b32 v[38:39], v75 offset0:132 offset1:165
	v_lshl_add_u64 v[42:43], v[12:13], 0, s[72:73]
	v_lshlrev_b32_e32 v2, 12, v2
	s_waitcnt lgkmcnt(0)
	v_cvt_pk_bf16_f32 v38, v38, v39
	ds_read2_b32 v[40:41], v75 offset0:198 offset1:231
	s_waitcnt lgkmcnt(0)
	v_cvt_pk_bf16_f32 v39, v40, v41
	v_lshl_add_u64 v[44:45], v[42:43], 0, v[2:3]
	ds_read2_b32 v[40:41], v75 offset0:8 offset1:41
	global_store_dwordx4 v[44:45], v[36:39], off sc1
	v_or_b32_e32 v2, s2, v76
	v_lshlrev_b32_e32 v2, 12, v2
	s_waitcnt lgkmcnt(0)
	v_cvt_pk_bf16_f32 v36, v40, v41
	ds_read2_b32 v[38:39], v75 offset0:74 offset1:107
	s_waitcnt lgkmcnt(0)
	v_cvt_pk_bf16_f32 v37, v38, v39
	ds_read2_b32 v[38:39], v75 offset0:140 offset1:173
	s_waitcnt lgkmcnt(0)
	v_cvt_pk_bf16_f32 v38, v38, v39
	ds_read2_b32 v[40:41], v75 offset0:206 offset1:239
	s_waitcnt lgkmcnt(0)
	v_cvt_pk_bf16_f32 v39, v40, v41
	v_lshl_add_u64 v[44:45], v[42:43], 0, v[2:3]
	ds_read2_b32 v[40:41], v75 offset0:16 offset1:49
	global_store_dwordx4 v[44:45], v[36:39], off sc1
	v_or_b32_e32 v2, s2, v77
	v_lshlrev_b32_e32 v2, 12, v2
	s_waitcnt lgkmcnt(0)
	v_cvt_pk_bf16_f32 v36, v40, v41
	ds_read2_b32 v[38:39], v75 offset0:82 offset1:115
	s_waitcnt lgkmcnt(0)
	v_cvt_pk_bf16_f32 v37, v38, v39
	ds_read2_b32 v[38:39], v75 offset0:148 offset1:181
	s_waitcnt lgkmcnt(0)
	v_cvt_pk_bf16_f32 v38, v38, v39
	ds_read2_b32 v[40:41], v75 offset0:214 offset1:247
	s_waitcnt lgkmcnt(0)
	v_cvt_pk_bf16_f32 v39, v40, v41
	v_lshl_add_u64 v[44:45], v[42:43], 0, v[2:3]
	ds_read2_b32 v[40:41], v75 offset0:24 offset1:57
	global_store_dwordx4 v[44:45], v[36:39], off sc1
	v_or_b32_e32 v2, s2, v78
	v_lshlrev_b32_e32 v2, 12, v2
	s_waitcnt lgkmcnt(0)
	v_cvt_pk_bf16_f32 v36, v40, v41
	ds_read2_b32 v[38:39], v75 offset0:90 offset1:123
	s_waitcnt lgkmcnt(0)
	v_cvt_pk_bf16_f32 v37, v38, v39
	ds_read2_b32 v[38:39], v75 offset0:156 offset1:189
	s_waitcnt lgkmcnt(0)
	v_cvt_pk_bf16_f32 v38, v38, v39
	ds_read2_b32 v[40:41], v75 offset0:222 offset1:255
	s_waitcnt lgkmcnt(0)
	v_cvt_pk_bf16_f32 v39, v40, v41
	v_lshl_add_u64 v[40:41], v[42:43], 0, v[2:3]
	global_store_dwordx4 v[40:41], v[36:39], off sc1
	s_waitcnt lgkmcnt(0)

.LBB0_73:
	s_andn2_b64 vcc, exec, s[0:1]
	s_cbranch_vccnz .LBB0_75
	s_add_i32 s1, s75, 0xffffe100
	s_lshr_b32 s1, s1, 1
	s_add_i32 s0, s26, 0xfffffc00
	s_and_b32 s1, s1, 0x7fffffc0
	s_and_b32 s0, s0, 0xfe0
	v_or_b32_e32 v2, s1, v56
	s_lshl_b32 s72, s0, 2
	v_or_b32_e32 v40, 2, v2
	v_mov_b32_e32 v41, v3
	v_or_b32_e32 v42, 4, v2
	v_mov_b32_e32 v43, v3
	v_or_b32_e32 v44, 6, v2
	v_mov_b32_e32 v45, v3
	v_or_b32_e32 v46, 8, v2
	v_mov_b32_e32 v47, v3
	v_or_b32_e32 v48, 10, v2
	v_mov_b32_e32 v49, v3
	v_or_b32_e32 v50, 12, v2
	v_mov_b32_e32 v51, v3
	v_lshl_add_u64 v[36:37], v[14:15], 0, s[72:73]
	v_lshlrev_b64 v[38:39], 14, v[2:3]
	v_lshlrev_b64 v[40:41], 14, v[40:41]
	v_lshlrev_b64 v[42:43], 14, v[42:43]
	v_lshlrev_b64 v[44:45], 14, v[44:45]
	v_lshlrev_b64 v[46:47], 14, v[46:47]
	v_lshlrev_b64 v[48:49], 14, v[48:49]
	v_lshlrev_b64 v[50:51], 14, v[50:51]
	v_or_b32_e32 v52, 14, v2
	v_mov_b32_e32 v53, v3
	v_lshl_add_u64 v[38:39], v[36:37], 0, v[38:39]
	v_lshl_add_u64 v[40:41], v[36:37], 0, v[40:41]
	v_lshl_add_u64 v[42:43], v[36:37], 0, v[42:43]
	v_lshl_add_u64 v[44:45], v[36:37], 0, v[44:45]
	v_lshl_add_u64 v[46:47], v[36:37], 0, v[46:47]
	v_lshl_add_u64 v[48:49], v[36:37], 0, v[48:49]
	v_lshl_add_u64 v[50:51], v[36:37], 0, v[50:51]
	v_lshlrev_b64 v[52:53], 14, v[52:53]
	v_lshl_add_u64 v[52:53], v[36:37], 0, v[52:53]
	global_load_dword v33, v[38:39], off
	global_load_dword v35, v[40:41], off
	global_load_dword v54, v[42:43], off
	global_load_dword v55, v[44:45], off
	global_load_dword v79, v[46:47], off
	global_load_dword v80, v[48:49], off
	global_load_dword v81, v[50:51], off
	global_load_dword v82, v[52:53], off
	v_or_b32_e32 v38, 16, v2
	v_mov_b32_e32 v39, v3
	v_or_b32_e32 v40, 18, v2
	v_mov_b32_e32 v41, v3
	v_or_b32_e32 v42, 20, v2
	v_mov_b32_e32 v43, v3
	v_or_b32_e32 v44, 22, v2
	v_mov_b32_e32 v45, v3
	v_or_b32_e32 v46, 24, v2
	v_mov_b32_e32 v47, v3
	v_or_b32_e32 v48, 26, v2
	v_mov_b32_e32 v49, v3
	v_or_b32_e32 v50, 28, v2
	v_mov_b32_e32 v51, v3
	v_lshlrev_b64 v[38:39], 14, v[38:39]
	v_lshlrev_b64 v[40:41], 14, v[40:41]
	v_lshlrev_b64 v[42:43], 14, v[42:43]
	v_lshlrev_b64 v[44:45], 14, v[44:45]
	v_lshlrev_b64 v[46:47], 14, v[46:47]
	v_lshlrev_b64 v[48:49], 14, v[48:49]
	v_lshlrev_b64 v[50:51], 14, v[50:51]
	v_or_b32_e32 v52, 30, v2
	v_mov_b32_e32 v53, v3
	v_lshl_add_u64 v[38:39], v[36:37], 0, v[38:39]
	v_lshl_add_u64 v[40:41], v[36:37], 0, v[40:41]
	v_lshl_add_u64 v[42:43], v[36:37], 0, v[42:43]
	v_lshl_add_u64 v[44:45], v[36:37], 0, v[44:45]
	v_lshl_add_u64 v[46:47], v[36:37], 0, v[46:47]
	v_lshl_add_u64 v[48:49], v[36:37], 0, v[48:49]
	v_lshl_add_u64 v[50:51], v[36:37], 0, v[50:51]
	v_lshlrev_b64 v[52:53], 14, v[52:53]
	v_lshl_add_u64 v[52:53], v[36:37], 0, v[52:53]
	global_load_dword v83, v[38:39], off
	global_load_dword v84, v[40:41], off
	global_load_dword v85, v[42:43], off
	global_load_dword v86, v[44:45], off
	global_load_dword v87, v[46:47], off
	global_load_dword v88, v[48:49], off
	global_load_dword v89, v[50:51], off
	global_load_dword v90, v[52:53], off
	v_or_b32_e32 v38, 32, v2
	v_mov_b32_e32 v39, v3
	v_or_b32_e32 v40, 34, v2
	v_mov_b32_e32 v41, v3
	v_or_b32_e32 v42, 36, v2
	v_mov_b32_e32 v43, v3
	v_or_b32_e32 v44, 38, v2
	v_mov_b32_e32 v45, v3
	v_or_b32_e32 v46, 40, v2
	v_mov_b32_e32 v47, v3
	v_or_b32_e32 v48, 42, v2
	v_mov_b32_e32 v49, v3
	v_or_b32_e32 v50, 44, v2
	v_mov_b32_e32 v51, v3
	v_lshlrev_b64 v[38:39], 14, v[38:39]
	v_lshlrev_b64 v[40:41], 14, v[40:41]
	v_lshlrev_b64 v[42:43], 14, v[42:43]
	v_lshlrev_b64 v[44:45], 14, v[44:45]
	v_lshlrev_b64 v[46:47], 14, v[46:47]
	v_lshlrev_b64 v[48:49], 14, v[48:49]
	v_lshlrev_b64 v[50:51], 14, v[50:51]
	v_or_b32_e32 v52, 46, v2
	v_mov_b32_e32 v53, v3
	v_lshl_add_u64 v[38:39], v[36:37], 0, v[38:39]
	v_lshl_add_u64 v[40:41], v[36:37], 0, v[40:41]
	v_lshl_add_u64 v[42:43], v[36:37], 0, v[42:43]
	v_lshl_add_u64 v[44:45], v[36:37], 0, v[44:45]
	v_lshl_add_u64 v[46:47], v[36:37], 0, v[46:47]
	v_lshl_add_u64 v[48:49], v[36:37], 0, v[48:49]
	v_lshl_add_u64 v[50:51], v[36:37], 0, v[50:51]
	v_lshlrev_b64 v[52:53], 14, v[52:53]
	v_lshl_add_u64 v[52:53], v[36:37], 0, v[52:53]
	global_load_dword v91, v[38:39], off
	global_load_dword v92, v[40:41], off
	global_load_dword v93, v[42:43], off
	global_load_dword v94, v[44:45], off
	global_load_dword v95, v[46:47], off
	global_load_dword v96, v[48:49], off
	global_load_dword v97, v[50:51], off
	global_load_dword v98, v[52:53], off
	v_or_b32_e32 v38, 48, v2
	v_mov_b32_e32 v39, v3
	v_or_b32_e32 v40, 50, v2
	v_mov_b32_e32 v41, v3
	v_or_b32_e32 v42, 52, v2
	v_mov_b32_e32 v43, v3
	v_or_b32_e32 v44, 54, v2
	v_mov_b32_e32 v45, v3
	v_or_b32_e32 v46, 56, v2
	v_mov_b32_e32 v47, v3
	v_or_b32_e32 v48, 58, v2
	v_mov_b32_e32 v49, v3
	v_or_b32_e32 v50, 60, v2
	v_mov_b32_e32 v51, v3
	v_or_b32_e32 v2, 62, v2
	v_lshlrev_b64 v[38:39], 14, v[38:39]
	v_lshlrev_b64 v[40:41], 14, v[40:41]
	v_lshlrev_b64 v[42:43], 14, v[42:43]
	v_lshlrev_b64 v[44:45], 14, v[44:45]
	v_lshlrev_b64 v[46:47], 14, v[46:47]
	v_lshlrev_b64 v[48:49], 14, v[48:49]
	v_lshlrev_b64 v[50:51], 14, v[50:51]
	v_lshlrev_b64 v[52:53], 14, v[2:3]
	v_lshl_add_u64 v[38:39], v[36:37], 0, v[38:39]
	v_lshl_add_u64 v[40:41], v[36:37], 0, v[40:41]
	v_lshl_add_u64 v[42:43], v[36:37], 0, v[42:43]
	v_lshl_add_u64 v[44:45], v[36:37], 0, v[44:45]
	v_lshl_add_u64 v[46:47], v[36:37], 0, v[46:47]
	v_lshl_add_u64 v[48:49], v[36:37], 0, v[48:49]
	v_lshl_add_u64 v[50:51], v[36:37], 0, v[50:51]
	v_lshl_add_u64 v[36:37], v[36:37], 0, v[52:53]
	global_load_dword v2, v[38:39], off
	s_nop 0
	global_load_dword v38, v[40:41], off
	global_load_dword v39, v[42:43], off
	s_nop 0
	global_load_dword v40, v[44:45], off
	global_load_dword v41, v[46:47], off
	global_load_dword v42, v[48:49], off
	global_load_dword v43, v[50:51], off
	s_nop 0
	global_load_dword v36, v[36:37], off
	s_waitcnt vmcnt(30)
	ds_write2_b32 v58, v33, v35 offset1:66
	s_waitcnt vmcnt(28)
	ds_write2_b32 v58, v54, v55 offset0:132 offset1:198
	v_add_u32_e32 v33, 0x400, v58
	s_waitcnt vmcnt(26)
	ds_write2_b32 v33, v79, v80 offset0:8 offset1:74
	s_waitcnt vmcnt(24)
	ds_write2_b32 v33, v81, v82 offset0:140 offset1:206
	v_add_u32_e32 v33, 0x800, v58
	s_waitcnt vmcnt(22)
	ds_write2_b32 v33, v83, v84 offset0:16 offset1:82
	s_waitcnt vmcnt(20)
	ds_write2_b32 v33, v85, v86 offset0:148 offset1:214
	v_add_u32_e32 v33, 0xc00, v58
	s_waitcnt vmcnt(18)
	ds_write2_b32 v33, v87, v88 offset0:24 offset1:90
	s_waitcnt vmcnt(16)
	ds_write2_b32 v33, v89, v90 offset0:156 offset1:222
	v_add_u32_e32 v33, 0x1000, v58
	s_waitcnt vmcnt(14)
	ds_write2_b32 v33, v91, v92 offset0:32 offset1:98
	s_waitcnt vmcnt(12)
	ds_write2_b32 v33, v93, v94 offset0:164 offset1:230
	v_add_u32_e32 v33, 0x1400, v58
	s_waitcnt vmcnt(10)
	ds_write2_b32 v33, v95, v96 offset0:40 offset1:106
	s_waitcnt vmcnt(8)
	ds_write2_b32 v33, v97, v98 offset0:172 offset1:238
	v_add_u32_e32 v33, 0x1800, v58
	s_waitcnt vmcnt(6)
	ds_write2_b32 v33, v2, v38 offset0:48 offset1:114
	s_waitcnt vmcnt(4)
	ds_write2_b32 v33, v39, v40 offset0:180 offset1:246
	v_add_u32_e32 v2, 0x1c00, v58
	s_waitcnt vmcnt(2)
	ds_write2_b32 v2, v41, v42 offset0:56 offset1:122
	s_waitcnt vmcnt(0)
	ds_write2_b32 v2, v43, v36 offset0:188 offset1:254
	s_waitcnt lgkmcnt(0)
	ds_read2_b32 v[36:37], v75 offset1:33
	s_waitcnt lgkmcnt(0)
	v_cvt_pk_bf16_f32 v36, v36, v37
	ds_read2_b32 v[38:39], v75 offset0:66 offset1:99
	s_lshl_b32 s72, s1, 1
	v_or_b32_e32 v2, s0, v74
	s_waitcnt lgkmcnt(0)
	v_cvt_pk_bf16_f32 v37, v38, v39
	ds_read2_b32 v[38:39], v75 offset0:132 offset1:165
	v_lshl_add_u64 v[42:43], v[16:17], 0, s[72:73]
	v_lshlrev_b32_e32 v2, 12, v2
	s_waitcnt lgkmcnt(0)
	v_cvt_pk_bf16_f32 v38, v38, v39
	ds_read2_b32 v[40:41], v75 offset0:198 offset1:231
	s_waitcnt lgkmcnt(0)
	v_cvt_pk_bf16_f32 v39, v40, v41
	v_lshl_add_u64 v[44:45], v[42:43], 0, v[2:3]
	ds_read2_b32 v[40:41], v75 offset0:8 offset1:41
	global_store_dwordx4 v[44:45], v[36:39], off sc1
	v_or_b32_e32 v2, s0, v76
	v_lshlrev_b32_e32 v2, 12, v2
	s_waitcnt lgkmcnt(0)
	v_cvt_pk_bf16_f32 v36, v40, v41
	ds_read2_b32 v[38:39], v75 offset0:74 offset1:107
	s_waitcnt lgkmcnt(0)
	v_cvt_pk_bf16_f32 v37, v38, v39
	ds_read2_b32 v[38:39], v75 offset0:140 offset1:173
	s_waitcnt lgkmcnt(0)
	v_cvt_pk_bf16_f32 v38, v38, v39
	ds_read2_b32 v[40:41], v75 offset0:206 offset1:239
	s_waitcnt lgkmcnt(0)
	v_cvt_pk_bf16_f32 v39, v40, v41
	v_lshl_add_u64 v[44:45], v[42:43], 0, v[2:3]
	ds_read2_b32 v[40:41], v75 offset0:16 offset1:49
	global_store_dwordx4 v[44:45], v[36:39], off sc1
	v_or_b32_e32 v2, s0, v77
	v_lshlrev_b32_e32 v2, 12, v2
	s_waitcnt lgkmcnt(0)
	v_cvt_pk_bf16_f32 v36, v40, v41
	ds_read2_b32 v[38:39], v75 offset0:82 offset1:115
	s_waitcnt lgkmcnt(0)
	v_cvt_pk_bf16_f32 v37, v38, v39
	ds_read2_b32 v[38:39], v75 offset0:148 offset1:181
	s_waitcnt lgkmcnt(0)
	v_cvt_pk_bf16_f32 v38, v38, v39
	ds_read2_b32 v[40:41], v75 offset0:214 offset1:247
	s_waitcnt lgkmcnt(0)
	v_cvt_pk_bf16_f32 v39, v40, v41
	v_lshl_add_u64 v[44:45], v[42:43], 0, v[2:3]
	ds_read2_b32 v[40:41], v75 offset0:24 offset1:57
	global_store_dwordx4 v[44:45], v[36:39], off sc1
	v_or_b32_e32 v2, s0, v78
	v_lshlrev_b32_e32 v2, 12, v2
	s_waitcnt lgkmcnt(0)
	v_cvt_pk_bf16_f32 v36, v40, v41
	ds_read2_b32 v[38:39], v75 offset0:90 offset1:123
	s_waitcnt lgkmcnt(0)
	v_cvt_pk_bf16_f32 v37, v38, v39
	ds_read2_b32 v[38:39], v75 offset0:156 offset1:189
	s_waitcnt lgkmcnt(0)
	v_cvt_pk_bf16_f32 v38, v38, v39
	ds_read2_b32 v[40:41], v75 offset0:222 offset1:255
	s_waitcnt lgkmcnt(0)
	v_cvt_pk_bf16_f32 v39, v40, v41
	v_lshl_add_u64 v[40:41], v[42:43], 0, v[2:3]
	global_store_dwordx4 v[40:41], v[36:39], off sc1
	s_waitcnt lgkmcnt(0)

.LBB0_76:
	s_andn2_b64 vcc, exec, s[0:1]
	s_cbranch_vccnz .LBB0_78
	s_and_b32 s0, s75, 0x1fc0
	s_addk_i32 s0, 0xe900
	s_add_i32 s1, s26, 0xfffffc00
	s_and_b32 s2, s1, 0x7e0
	v_or_b32_e32 v2, s0, v56
	s_lshl_b32 s72, s2, 2
	v_or_b32_e32 v40, 2, v2
	v_mov_b32_e32 v41, v3
	v_or_b32_e32 v42, 4, v2
	v_mov_b32_e32 v43, v3
	v_or_b32_e32 v44, 6, v2
	v_mov_b32_e32 v45, v3
	v_or_b32_e32 v46, 8, v2
	v_mov_b32_e32 v47, v3
	v_or_b32_e32 v48, 10, v2
	v_mov_b32_e32 v49, v3
	v_or_b32_e32 v50, 12, v2
	v_mov_b32_e32 v51, v3
	v_lshl_add_u64 v[36:37], v[18:19], 0, s[72:73]
	v_lshlrev_b64 v[38:39], 13, v[2:3]
	v_lshlrev_b64 v[40:41], 13, v[40:41]
	v_lshlrev_b64 v[42:43], 13, v[42:43]
	v_lshlrev_b64 v[44:45], 13, v[44:45]
	v_lshlrev_b64 v[46:47], 13, v[46:47]
	v_lshlrev_b64 v[48:49], 13, v[48:49]
	v_lshlrev_b64 v[50:51], 13, v[50:51]
	v_or_b32_e32 v52, 14, v2
	v_mov_b32_e32 v53, v3
	v_lshl_add_u64 v[38:39], v[36:37], 0, v[38:39]
	v_lshl_add_u64 v[40:41], v[36:37], 0, v[40:41]
	v_lshl_add_u64 v[42:43], v[36:37], 0, v[42:43]
	v_lshl_add_u64 v[44:45], v[36:37], 0, v[44:45]
	v_lshl_add_u64 v[46:47], v[36:37], 0, v[46:47]
	v_lshl_add_u64 v[48:49], v[36:37], 0, v[48:49]
	v_lshl_add_u64 v[50:51], v[36:37], 0, v[50:51]
	v_lshlrev_b64 v[52:53], 13, v[52:53]
	v_lshl_add_u64 v[52:53], v[36:37], 0, v[52:53]
	global_load_dword v33, v[38:39], off
	global_load_dword v35, v[40:41], off
	global_load_dword v54, v[42:43], off
	global_load_dword v55, v[44:45], off
	global_load_dword v79, v[46:47], off
	global_load_dword v80, v[48:49], off
	global_load_dword v81, v[50:51], off
	global_load_dword v82, v[52:53], off
	v_or_b32_e32 v38, 16, v2
	v_mov_b32_e32 v39, v3
	v_or_b32_e32 v40, 18, v2
	v_mov_b32_e32 v41, v3
	v_or_b32_e32 v42, 20, v2
	v_mov_b32_e32 v43, v3
	v_or_b32_e32 v44, 22, v2
	v_mov_b32_e32 v45, v3
	v_or_b32_e32 v46, 24, v2
	v_mov_b32_e32 v47, v3
	v_or_b32_e32 v48, 26, v2
	v_mov_b32_e32 v49, v3
	v_or_b32_e32 v50, 28, v2
	v_mov_b32_e32 v51, v3
	v_lshlrev_b64 v[38:39], 13, v[38:39]
	v_lshlrev_b64 v[40:41], 13, v[40:41]
	v_lshlrev_b64 v[42:43], 13, v[42:43]
	v_lshlrev_b64 v[44:45], 13, v[44:45]
	v_lshlrev_b64 v[46:47], 13, v[46:47]
	v_lshlrev_b64 v[48:49], 13, v[48:49]
	v_lshlrev_b64 v[50:51], 13, v[50:51]
	v_or_b32_e32 v52, 30, v2
	v_mov_b32_e32 v53, v3
	v_lshl_add_u64 v[38:39], v[36:37], 0, v[38:39]
	v_lshl_add_u64 v[40:41], v[36:37], 0, v[40:41]
	v_lshl_add_u64 v[42:43], v[36:37], 0, v[42:43]
	v_lshl_add_u64 v[44:45], v[36:37], 0, v[44:45]
	v_lshl_add_u64 v[46:47], v[36:37], 0, v[46:47]
	v_lshl_add_u64 v[48:49], v[36:37], 0, v[48:49]
	v_lshl_add_u64 v[50:51], v[36:37], 0, v[50:51]
	v_lshlrev_b64 v[52:53], 13, v[52:53]
	v_lshl_add_u64 v[52:53], v[36:37], 0, v[52:53]
	global_load_dword v83, v[38:39], off
	global_load_dword v84, v[40:41], off
	global_load_dword v85, v[42:43], off
	global_load_dword v86, v[44:45], off
	global_load_dword v87, v[46:47], off
	global_load_dword v88, v[48:49], off
	global_load_dword v89, v[50:51], off
	global_load_dword v90, v[52:53], off
	v_or_b32_e32 v38, 32, v2
	v_mov_b32_e32 v39, v3
	v_or_b32_e32 v40, 34, v2
	v_mov_b32_e32 v41, v3
	v_or_b32_e32 v42, 36, v2
	v_mov_b32_e32 v43, v3
	v_or_b32_e32 v44, 38, v2
	v_mov_b32_e32 v45, v3
	v_or_b32_e32 v46, 40, v2
	v_mov_b32_e32 v47, v3
	v_or_b32_e32 v48, 42, v2
	v_mov_b32_e32 v49, v3
	v_or_b32_e32 v50, 44, v2
	v_mov_b32_e32 v51, v3
	v_lshlrev_b64 v[38:39], 13, v[38:39]
	v_lshlrev_b64 v[40:41], 13, v[40:41]
	v_lshlrev_b64 v[42:43], 13, v[42:43]
	v_lshlrev_b64 v[44:45], 13, v[44:45]
	v_lshlrev_b64 v[46:47], 13, v[46:47]
	v_lshlrev_b64 v[48:49], 13, v[48:49]
	v_lshlrev_b64 v[50:51], 13, v[50:51]
	v_or_b32_e32 v52, 46, v2
	v_mov_b32_e32 v53, v3
	v_lshl_add_u64 v[38:39], v[36:37], 0, v[38:39]
	v_lshl_add_u64 v[40:41], v[36:37], 0, v[40:41]
	v_lshl_add_u64 v[42:43], v[36:37], 0, v[42:43]
	v_lshl_add_u64 v[44:45], v[36:37], 0, v[44:45]
	v_lshl_add_u64 v[46:47], v[36:37], 0, v[46:47]
	v_lshl_add_u64 v[48:49], v[36:37], 0, v[48:49]
	v_lshl_add_u64 v[50:51], v[36:37], 0, v[50:51]
	v_lshlrev_b64 v[52:53], 13, v[52:53]
	v_lshl_add_u64 v[52:53], v[36:37], 0, v[52:53]
	global_load_dword v91, v[38:39], off
	global_load_dword v92, v[40:41], off
	global_load_dword v93, v[42:43], off
	global_load_dword v94, v[44:45], off
	global_load_dword v95, v[46:47], off
	global_load_dword v96, v[48:49], off
	global_load_dword v97, v[50:51], off
	global_load_dword v98, v[52:53], off
	v_or_b32_e32 v38, 48, v2
	v_mov_b32_e32 v39, v3
	v_or_b32_e32 v40, 50, v2
	v_mov_b32_e32 v41, v3
	v_or_b32_e32 v42, 52, v2
	v_mov_b32_e32 v43, v3
	v_or_b32_e32 v44, 54, v2
	v_mov_b32_e32 v45, v3
	v_or_b32_e32 v46, 56, v2
	v_mov_b32_e32 v47, v3
	v_or_b32_e32 v48, 58, v2
	v_mov_b32_e32 v49, v3
	v_or_b32_e32 v50, 60, v2
	v_mov_b32_e32 v51, v3
	v_or_b32_e32 v2, 62, v2
	v_lshlrev_b64 v[38:39], 13, v[38:39]
	v_lshlrev_b64 v[40:41], 13, v[40:41]
	v_lshlrev_b64 v[42:43], 13, v[42:43]
	v_lshlrev_b64 v[44:45], 13, v[44:45]
	v_lshlrev_b64 v[46:47], 13, v[46:47]
	v_lshlrev_b64 v[48:49], 13, v[48:49]
	v_lshlrev_b64 v[50:51], 13, v[50:51]
	v_lshlrev_b64 v[52:53], 13, v[2:3]
	v_lshl_add_u64 v[38:39], v[36:37], 0, v[38:39]
	v_lshl_add_u64 v[40:41], v[36:37], 0, v[40:41]
	v_lshl_add_u64 v[42:43], v[36:37], 0, v[42:43]
	v_lshl_add_u64 v[44:45], v[36:37], 0, v[44:45]
	v_lshl_add_u64 v[46:47], v[36:37], 0, v[46:47]
	v_lshl_add_u64 v[48:49], v[36:37], 0, v[48:49]
	v_lshl_add_u64 v[50:51], v[36:37], 0, v[50:51]
	v_lshl_add_u64 v[36:37], v[36:37], 0, v[52:53]
	global_load_dword v2, v[38:39], off
	s_nop 0
	global_load_dword v38, v[40:41], off
	global_load_dword v39, v[42:43], off
	s_nop 0
	global_load_dword v40, v[44:45], off
	global_load_dword v41, v[46:47], off
	global_load_dword v42, v[48:49], off
	global_load_dword v43, v[50:51], off
	s_nop 0
	global_load_dword v36, v[36:37], off
	s_waitcnt vmcnt(30)
	ds_write2_b32 v58, v33, v35 offset1:66
	s_waitcnt vmcnt(28)
	ds_write2_b32 v58, v54, v55 offset0:132 offset1:198
	v_add_u32_e32 v33, 0x400, v58
	s_waitcnt vmcnt(26)
	ds_write2_b32 v33, v79, v80 offset0:8 offset1:74
	s_waitcnt vmcnt(24)
	ds_write2_b32 v33, v81, v82 offset0:140 offset1:206
	v_add_u32_e32 v33, 0x800, v58
	s_waitcnt vmcnt(22)
	ds_write2_b32 v33, v83, v84 offset0:16 offset1:82
	s_waitcnt vmcnt(20)
	ds_write2_b32 v33, v85, v86 offset0:148 offset1:214
	v_add_u32_e32 v33, 0xc00, v58
	s_waitcnt vmcnt(18)
	ds_write2_b32 v33, v87, v88 offset0:24 offset1:90
	s_waitcnt vmcnt(16)
	ds_write2_b32 v33, v89, v90 offset0:156 offset1:222
	v_add_u32_e32 v33, 0x1000, v58
	s_waitcnt vmcnt(14)
	ds_write2_b32 v33, v91, v92 offset0:32 offset1:98
	s_waitcnt vmcnt(12)
	ds_write2_b32 v33, v93, v94 offset0:164 offset1:230
	v_add_u32_e32 v33, 0x1400, v58
	s_waitcnt vmcnt(10)
	ds_write2_b32 v33, v95, v96 offset0:40 offset1:106
	s_waitcnt vmcnt(8)
	ds_write2_b32 v33, v97, v98 offset0:172 offset1:238
	v_add_u32_e32 v33, 0x1800, v58
	s_waitcnt vmcnt(6)
	ds_write2_b32 v33, v2, v38 offset0:48 offset1:114
	s_waitcnt vmcnt(4)
	ds_write2_b32 v33, v39, v40 offset0:180 offset1:246
	v_add_u32_e32 v2, 0x1c00, v58
	s_waitcnt vmcnt(2)
	ds_write2_b32 v2, v41, v42 offset0:56 offset1:122
	s_waitcnt vmcnt(0)
	ds_write2_b32 v2, v43, v36 offset0:188 offset1:254
	s_waitcnt lgkmcnt(0)
	ds_read2_b32 v[36:37], v75 offset1:33
	s_waitcnt lgkmcnt(0)
	v_cvt_pk_bf16_f32 v36, v36, v37
	ds_read2_b32 v[38:39], v75 offset0:66 offset1:99
	s_mov_b32 s1, s73
	v_or_b32_e32 v2, s2, v74
	s_waitcnt lgkmcnt(0)
	v_cvt_pk_bf16_f32 v37, v38, v39
	ds_read2_b32 v[38:39], v75 offset0:132 offset1:165
	v_lshl_add_u64 v[42:43], s[0:1], 1, v[20:21]
	v_lshlrev_b32_e32 v2, 12, v2
	s_waitcnt lgkmcnt(0)
	v_cvt_pk_bf16_f32 v38, v38, v39
	ds_read2_b32 v[40:41], v75 offset0:198 offset1:231
	s_waitcnt lgkmcnt(0)
	v_cvt_pk_bf16_f32 v39, v40, v41
	v_lshl_add_u64 v[44:45], v[42:43], 0, v[2:3]
	ds_read2_b32 v[40:41], v75 offset0:8 offset1:41
	global_store_dwordx4 v[44:45], v[36:39], off sc1
	v_or_b32_e32 v2, s2, v76
	v_lshlrev_b32_e32 v2, 12, v2
	s_waitcnt lgkmcnt(0)
	v_cvt_pk_bf16_f32 v36, v40, v41
	ds_read2_b32 v[38:39], v75 offset0:74 offset1:107
	s_waitcnt lgkmcnt(0)
	v_cvt_pk_bf16_f32 v37, v38, v39
	ds_read2_b32 v[38:39], v75 offset0:140 offset1:173
	s_waitcnt lgkmcnt(0)
	v_cvt_pk_bf16_f32 v38, v38, v39
	ds_read2_b32 v[40:41], v75 offset0:206 offset1:239
	s_waitcnt lgkmcnt(0)
	v_cvt_pk_bf16_f32 v39, v40, v41
	v_lshl_add_u64 v[44:45], v[42:43], 0, v[2:3]
	ds_read2_b32 v[40:41], v75 offset0:16 offset1:49
	global_store_dwordx4 v[44:45], v[36:39], off sc1
	v_or_b32_e32 v2, s2, v77
	v_lshlrev_b32_e32 v2, 12, v2
	s_waitcnt lgkmcnt(0)
	v_cvt_pk_bf16_f32 v36, v40, v41
	ds_read2_b32 v[38:39], v75 offset0:82 offset1:115
	s_waitcnt lgkmcnt(0)
	v_cvt_pk_bf16_f32 v37, v38, v39
	ds_read2_b32 v[38:39], v75 offset0:148 offset1:181
	s_waitcnt lgkmcnt(0)
	v_cvt_pk_bf16_f32 v38, v38, v39
	ds_read2_b32 v[40:41], v75 offset0:214 offset1:247
	s_waitcnt lgkmcnt(0)
	v_cvt_pk_bf16_f32 v39, v40, v41
	v_lshl_add_u64 v[44:45], v[42:43], 0, v[2:3]
	ds_read2_b32 v[40:41], v75 offset0:24 offset1:57
	global_store_dwordx4 v[44:45], v[36:39], off sc1
	v_or_b32_e32 v2, s2, v78
	v_lshlrev_b32_e32 v2, 12, v2
	s_waitcnt lgkmcnt(0)
	v_cvt_pk_bf16_f32 v36, v40, v41
	ds_read2_b32 v[38:39], v75 offset0:90 offset1:123
	s_waitcnt lgkmcnt(0)
	v_cvt_pk_bf16_f32 v37, v38, v39
	ds_read2_b32 v[38:39], v75 offset0:156 offset1:189
	s_waitcnt lgkmcnt(0)
	v_cvt_pk_bf16_f32 v38, v38, v39
	ds_read2_b32 v[40:41], v75 offset0:222 offset1:255
	s_waitcnt lgkmcnt(0)
	v_cvt_pk_bf16_f32 v39, v40, v41
	v_lshl_add_u64 v[40:41], v[42:43], 0, v[2:3]
	global_store_dwordx4 v[40:41], v[36:39], off sc1
	s_waitcnt lgkmcnt(0)

.LBB0_104:
	ds_write2_b32 v2, v38, v39 offset0:140 offset1:206
	s_waitcnt lgkmcnt(0)
	s_waitcnt vmcnt(0)
	ds_read2_b32 v[36:37], v75 offset1:33
	s_waitcnt lgkmcnt(0)
	v_cvt_pk_bf16_f32 v36, v36, v37
	ds_read2_b32 v[38:39], v75 offset0:66 offset1:99
	v_or_b32_e32 v2, s2, v74
	s_waitcnt lgkmcnt(0)
	v_cvt_pk_bf16_f32 v37, v38, v39
	ds_read2_b32 v[38:39], v75 offset0:132 offset1:165
	v_lshl_add_u64 v[42:43], s[72:73], 1, v[24:25]
	v_lshlrev_b32_e32 v2, 12, v2
	s_waitcnt lgkmcnt(0)
	v_cvt_pk_bf16_f32 v38, v38, v39
	ds_read2_b32 v[40:41], v75 offset0:198 offset1:231
	s_waitcnt lgkmcnt(0)
	v_cvt_pk_bf16_f32 v39, v40, v41
	v_lshl_add_u64 v[44:45], v[42:43], 0, v[2:3]
	ds_read2_b32 v[40:41], v75 offset0:8 offset1:41
	global_store_dwordx4 v[44:45], v[36:39], off sc1
	v_or_b32_e32 v2, s2, v76
	v_lshlrev_b32_e32 v2, 12, v2
	s_waitcnt lgkmcnt(0)
	v_cvt_pk_bf16_f32 v36, v40, v41
	ds_read2_b32 v[38:39], v75 offset0:74 offset1:107
	s_waitcnt lgkmcnt(0)
	v_cvt_pk_bf16_f32 v37, v38, v39
	ds_read2_b32 v[38:39], v75 offset0:140 offset1:173
	s_waitcnt lgkmcnt(0)
	v_cvt_pk_bf16_f32 v38, v38, v39
	ds_read2_b32 v[40:41], v75 offset0:206 offset1:239
	s_waitcnt lgkmcnt(0)
	v_cvt_pk_bf16_f32 v39, v40, v41
	v_lshl_add_u64 v[44:45], v[42:43], 0, v[2:3]
	ds_read2_b32 v[40:41], v75 offset0:16 offset1:49
	global_store_dwordx4 v[44:45], v[36:39], off sc1
	v_or_b32_e32 v2, s2, v77
	v_lshlrev_b32_e32 v2, 12, v2
	s_waitcnt lgkmcnt(0)
	v_cvt_pk_bf16_f32 v36, v40, v41
	ds_read2_b32 v[38:39], v75 offset0:82 offset1:115
	s_waitcnt lgkmcnt(0)
	v_cvt_pk_bf16_f32 v37, v38, v39
	ds_read2_b32 v[38:39], v75 offset0:148 offset1:181
	s_waitcnt lgkmcnt(0)
	v_cvt_pk_bf16_f32 v38, v38, v39
	ds_read2_b32 v[40:41], v75 offset0:214 offset1:247
	s_waitcnt lgkmcnt(0)
	v_cvt_pk_bf16_f32 v39, v40, v41
	v_lshl_add_u64 v[44:45], v[42:43], 0, v[2:3]
	ds_read2_b32 v[40:41], v75 offset0:24 offset1:57
	global_store_dwordx4 v[44:45], v[36:39], off sc1
	v_or_b32_e32 v2, s2, v78
	v_lshlrev_b32_e32 v2, 12, v2
	s_waitcnt lgkmcnt(0)
	v_cvt_pk_bf16_f32 v36, v40, v41
	ds_read2_b32 v[38:39], v75 offset0:90 offset1:123
	s_waitcnt lgkmcnt(0)
	v_cvt_pk_bf16_f32 v37, v38, v39
	ds_read2_b32 v[38:39], v75 offset0:156 offset1:189
	s_waitcnt lgkmcnt(0)
	v_cvt_pk_bf16_f32 v38, v38, v39
	ds_read2_b32 v[40:41], v75 offset0:222 offset1:255
	s_waitcnt lgkmcnt(0)
	v_cvt_pk_bf16_f32 v39, v40, v41
	v_lshl_add_u64 v[40:41], v[42:43], 0, v[2:3]
	global_store_dwordx4 v[40:41], v[36:39], off sc1
	s_waitcnt lgkmcnt(0)

.LBB0_106:
	s_andn2_b64 vcc, exec, s[0:1]
	s_cbranch_vccnz .LBB0_108
	s_add_i32 s0, s26, 0xfffffc00
	s_and_b32 s0, s0, 0x3e0
	s_and_b32 s1, s65, 0x1fc0
	v_readlane_b32 s76, v252, 1
	s_add_i32 s72, s1, 0xffffea00
	s_lshl_b32 s1, s0, 2
	v_readlane_b32 s84, v252, 9
	v_readlane_b32 s85, v252, 10
	s_add_u32 s2, s84, s1
	s_addc_u32 s3, s85, 0
	v_mov_b32_e32 v35, v3
	v_or_b32_e32 v2, s72, v56
	v_lshl_add_u64 v[36:37], s[2:3], 0, v[34:35]
	v_lshl_add_u64 v[36:37], v[36:37], 0, s[8:9]
	v_or_b32_e32 v33, 2, v2
	v_mad_u64_u32 v[40:41], s[2:3], v33, s74, v[36:37]
	v_or_b32_e32 v33, 4, v2
	v_mad_u64_u32 v[42:43], s[2:3], v33, s74, v[36:37]
	v_or_b32_e32 v33, 6, v2
	v_mad_u64_u32 v[44:45], s[2:3], v33, s74, v[36:37]
	v_or_b32_e32 v33, 8, v2
	v_mad_u64_u32 v[46:47], s[2:3], v33, s74, v[36:37]
	v_or_b32_e32 v33, 10, v2
	v_mad_u64_u32 v[48:49], s[2:3], v33, s74, v[36:37]
	v_or_b32_e32 v33, 12, v2
	v_mad_u64_u32 v[50:51], s[2:3], v33, s74, v[36:37]
	v_or_b32_e32 v33, 14, v2
	v_mad_u64_u32 v[38:39], s[2:3], v2, s74, v[36:37]
	v_mad_u64_u32 v[52:53], s[2:3], v33, s74, v[36:37]
	global_load_dword v33, v[38:39], off
	global_load_dword v35, v[40:41], off
	global_load_dword v54, v[42:43], off
	global_load_dword v55, v[44:45], off
	global_load_dword v79, v[46:47], off
	global_load_dword v80, v[48:49], off
	global_load_dword v81, v[50:51], off
	global_load_dword v82, v[52:53], off
	v_or_b32_e32 v38, 16, v2
	v_or_b32_e32 v40, 18, v2
	v_or_b32_e32 v42, 20, v2
	v_or_b32_e32 v44, 22, v2
	v_or_b32_e32 v46, 24, v2
	v_or_b32_e32 v48, 26, v2
	v_or_b32_e32 v50, 28, v2
	v_or_b32_e32 v52, 30, v2
	v_mad_u64_u32 v[38:39], s[2:3], v38, s74, v[36:37]
	v_mad_u64_u32 v[40:41], s[2:3], v40, s74, v[36:37]
	v_mad_u64_u32 v[42:43], s[2:3], v42, s74, v[36:37]
	v_mad_u64_u32 v[44:45], s[2:3], v44, s74, v[36:37]
	v_mad_u64_u32 v[46:47], s[2:3], v46, s74, v[36:37]
	v_mad_u64_u32 v[48:49], s[2:3], v48, s74, v[36:37]
	v_mad_u64_u32 v[50:51], s[2:3], v50, s74, v[36:37]
	v_mad_u64_u32 v[52:53], s[2:3], v52, s74, v[36:37]
	global_load_dword v83, v[38:39], off
	global_load_dword v84, v[40:41], off
	global_load_dword v85, v[42:43], off
	global_load_dword v86, v[44:45], off
	global_load_dword v87, v[46:47], off
	global_load_dword v88, v[48:49], off
	global_load_dword v89, v[50:51], off
	global_load_dword v90, v[52:53], off
	v_or_b32_e32 v38, 32, v2
	v_or_b32_e32 v40, 34, v2
	v_or_b32_e32 v42, 36, v2
	v_or_b32_e32 v44, 38, v2
	v_or_b32_e32 v46, 40, v2
	v_or_b32_e32 v48, 42, v2
	v_or_b32_e32 v50, 44, v2
	v_or_b32_e32 v52, 46, v2
	v_mad_u64_u32 v[38:39], s[2:3], v38, s74, v[36:37]
	v_mad_u64_u32 v[40:41], s[2:3], v40, s74, v[36:37]
	v_mad_u64_u32 v[42:43], s[2:3], v42, s74, v[36:37]
	v_mad_u64_u32 v[44:45], s[2:3], v44, s74, v[36:37]
	v_mad_u64_u32 v[46:47], s[2:3], v46, s74, v[36:37]
	v_mad_u64_u32 v[48:49], s[2:3], v48, s74, v[36:37]
	v_mad_u64_u32 v[50:51], s[2:3], v50, s74, v[36:37]
	v_mad_u64_u32 v[52:53], s[2:3], v52, s74, v[36:37]
	global_load_dword v91, v[38:39], off
	global_load_dword v92, v[40:41], off
	global_load_dword v93, v[42:43], off
	global_load_dword v94, v[44:45], off
	global_load_dword v95, v[46:47], off
	global_load_dword v96, v[48:49], off
	global_load_dword v97, v[50:51], off
	s_nop 0
	global_load_dword v52, v[52:53], off
	v_or_b32_e32 v38, 48, v2
	v_or_b32_e32 v40, 50, v2
	v_or_b32_e32 v42, 52, v2
	v_or_b32_e32 v44, 54, v2
	v_or_b32_e32 v46, 56, v2
	v_or_b32_e32 v48, 58, v2
	v_or_b32_e32 v50, 60, v2
	v_or_b32_e32 v2, 62, v2
	v_mad_u64_u32 v[38:39], s[2:3], v38, s74, v[36:37]
	v_mad_u64_u32 v[40:41], s[2:3], v40, s74, v[36:37]
	v_mad_u64_u32 v[42:43], s[2:3], v42, s74, v[36:37]
	v_mad_u64_u32 v[44:45], s[2:3], v44, s74, v[36:37]
	v_mad_u64_u32 v[46:47], s[2:3], v46, s74, v[36:37]
	v_mad_u64_u32 v[48:49], s[2:3], v48, s74, v[36:37]
	v_mad_u64_u32 v[50:51], s[2:3], v50, s74, v[36:37]
	v_mad_u64_u32 v[36:37], s[2:3], v2, s74, v[36:37]
	global_load_dword v2, v[38:39], off
	s_nop 0
	global_load_dword v38, v[40:41], off
	global_load_dword v39, v[42:43], off
	s_nop 0
	global_load_dword v40, v[44:45], off
	global_load_dword v41, v[46:47], off
	global_load_dword v42, v[48:49], off
	global_load_dword v43, v[50:51], off
	s_nop 0
	global_load_dword v36, v[36:37], off
	s_waitcnt vmcnt(30)
	ds_write2_b32 v58, v33, v35 offset1:66
	s_waitcnt vmcnt(28)
	ds_write2_b32 v58, v54, v55 offset0:132 offset1:198
	v_add_u32_e32 v33, 0x400, v58
	s_waitcnt vmcnt(26)
	ds_write2_b32 v33, v79, v80 offset0:8 offset1:74
	s_waitcnt vmcnt(24)
	ds_write2_b32 v33, v81, v82 offset0:140 offset1:206
	v_add_u32_e32 v33, 0x800, v58
	s_waitcnt vmcnt(22)
	ds_write2_b32 v33, v83, v84 offset0:16 offset1:82
	s_waitcnt vmcnt(20)
	ds_write2_b32 v33, v85, v86 offset0:148 offset1:214
	v_add_u32_e32 v33, 0xc00, v58
	s_waitcnt vmcnt(18)
	ds_write2_b32 v33, v87, v88 offset0:24 offset1:90
	s_waitcnt vmcnt(16)
	ds_write2_b32 v33, v89, v90 offset0:156 offset1:222
	v_add_u32_e32 v33, 0x1000, v58
	s_waitcnt vmcnt(14)
	ds_write2_b32 v33, v91, v92 offset0:32 offset1:98
	s_waitcnt vmcnt(12)
	ds_write2_b32 v33, v93, v94 offset0:164 offset1:230
	v_add_u32_e32 v33, 0x1400, v58
	s_waitcnt vmcnt(10)
	ds_write2_b32 v33, v95, v96 offset0:40 offset1:106
	s_waitcnt vmcnt(8)
	ds_write2_b32 v33, v97, v52 offset0:172 offset1:238
	v_add_u32_e32 v33, 0x1800, v58
	s_waitcnt vmcnt(6)
	ds_write2_b32 v33, v2, v38 offset0:48 offset1:114
	s_waitcnt vmcnt(4)
	ds_write2_b32 v33, v39, v40 offset0:180 offset1:246
	v_add_u32_e32 v2, 0x1c00, v58
	s_waitcnt vmcnt(2)
	ds_write2_b32 v2, v41, v42 offset0:56 offset1:122
	s_waitcnt vmcnt(0)
	ds_write2_b32 v2, v43, v36 offset0:188 offset1:254
	s_waitcnt lgkmcnt(0)
	ds_read2_b32 v[36:37], v75 offset1:33
	s_waitcnt lgkmcnt(0)
	v_cvt_pk_bf16_f32 v36, v36, v37
	ds_read2_b32 v[38:39], v75 offset0:66 offset1:99
	v_or_b32_e32 v2, s0, v74
	s_waitcnt lgkmcnt(0)
	v_cvt_pk_bf16_f32 v37, v38, v39
	ds_read2_b32 v[38:39], v75 offset0:132 offset1:165
	v_lshl_add_u64 v[42:43], s[72:73], 1, v[26:27]
	v_lshlrev_b32_e32 v2, 12, v2
	s_waitcnt lgkmcnt(0)
	v_cvt_pk_bf16_f32 v38, v38, v39
	ds_read2_b32 v[40:41], v75 offset0:198 offset1:231
	s_waitcnt lgkmcnt(0)
	v_cvt_pk_bf16_f32 v39, v40, v41
	v_lshl_add_u64 v[44:45], v[42:43], 0, v[2:3]
	ds_read2_b32 v[40:41], v75 offset0:8 offset1:41
	global_store_dwordx4 v[44:45], v[36:39], off sc1
	v_or_b32_e32 v2, s0, v76
	v_lshlrev_b32_e32 v2, 12, v2
	s_waitcnt lgkmcnt(0)
	v_cvt_pk_bf16_f32 v36, v40, v41
	ds_read2_b32 v[38:39], v75 offset0:74 offset1:107
	s_waitcnt lgkmcnt(0)
	v_cvt_pk_bf16_f32 v37, v38, v39
	ds_read2_b32 v[38:39], v75 offset0:140 offset1:173
	s_waitcnt lgkmcnt(0)
	v_cvt_pk_bf16_f32 v38, v38, v39
	ds_read2_b32 v[40:41], v75 offset0:206 offset1:239
	s_waitcnt lgkmcnt(0)
	v_cvt_pk_bf16_f32 v39, v40, v41
	v_lshl_add_u64 v[44:45], v[42:43], 0, v[2:3]
	ds_read2_b32 v[40:41], v75 offset0:16 offset1:49
	global_store_dwordx4 v[44:45], v[36:39], off sc1
	v_or_b32_e32 v2, s0, v77
	v_lshlrev_b32_e32 v2, 12, v2
	s_waitcnt lgkmcnt(0)
	v_cvt_pk_bf16_f32 v36, v40, v41
	ds_read2_b32 v[38:39], v75 offset0:82 offset1:115
	s_waitcnt lgkmcnt(0)
	v_cvt_pk_bf16_f32 v37, v38, v39
	ds_read2_b32 v[38:39], v75 offset0:148 offset1:181
	s_waitcnt lgkmcnt(0)
	v_cvt_pk_bf16_f32 v38, v38, v39
	ds_read2_b32 v[40:41], v75 offset0:214 offset1:247
	s_waitcnt lgkmcnt(0)
	v_cvt_pk_bf16_f32 v39, v40, v41
	v_lshl_add_u64 v[44:45], v[42:43], 0, v[2:3]
	ds_read2_b32 v[40:41], v75 offset0:24 offset1:57
	global_store_dwordx4 v[44:45], v[36:39], off sc1
	v_or_b32_e32 v2, s0, v78
	v_lshlrev_b32_e32 v2, 12, v2
	s_waitcnt lgkmcnt(0)
	v_cvt_pk_bf16_f32 v36, v40, v41
	ds_read2_b32 v[38:39], v75 offset0:90 offset1:123
	s_waitcnt lgkmcnt(0)
	v_cvt_pk_bf16_f32 v37, v38, v39
	ds_read2_b32 v[38:39], v75 offset0:156 offset1:189
	s_waitcnt lgkmcnt(0)
	v_cvt_pk_bf16_f32 v38, v38, v39
	ds_read2_b32 v[40:41], v75 offset0:222 offset1:255
	s_waitcnt lgkmcnt(0)
	v_cvt_pk_bf16_f32 v39, v40, v41
	v_lshl_add_u64 v[40:41], v[42:43], 0, v[2:3]
	global_store_dwordx4 v[40:41], v[36:39], off sc1
	s_waitcnt lgkmcnt(0)
	v_readlane_b32 s77, v252, 2
	v_readlane_b32 s78, v252, 3
	v_readlane_b32 s79, v252, 4
	v_readlane_b32 s80, v252, 5
	v_readlane_b32 s81, v252, 6
	v_readlane_b32 s82, v252, 7
	v_readlane_b32 s83, v252, 8
	v_readlane_b32 s86, v252, 11
	v_readlane_b32 s87, v252, 12
	v_readlane_b32 s88, v252, 13
	v_readlane_b32 s89, v252, 14
	v_readlane_b32 s90, v252, 15
	v_readlane_b32 s91, v252, 16

.LBB0_109:
	s_andn2_b64 vcc, exec, s[0:1]
	s_cbranch_vccnz .LBB0_10
	s_mul_hi_i32 s0, s75, 0x2e8ba2e9
	s_lshr_b32 s1, s0, 31
	s_ashr_i32 s0, s0, 4
	s_add_i32 s0, s0, s1
	s_mul_i32 s2, s0, 0xfffff500
	s_mul_i32 s1, s0, 0xffffffa8
	s_add_i32 s10, s26, s2
	s_add_i32 s1, s75, s1
	s_add_i32 s2, s10, 0xfffffc00
	s_cmp_lt_i32 s1, 64
	s_cselect_b32 s2, s2, s10
	s_lshl_b32 s0, s0, 6
	v_or_b32_e32 v2, s0, v56
	s_ashr_i32 s3, s2, 31
	v_lshl_add_u64 v[36:37], s[2:3], 2, v[28:29]
	v_or_b32_e32 v33, 2, v2
	v_mad_i64_i32 v[40:41], s[2:3], v33, s74, v[36:37]
	v_or_b32_e32 v33, 4, v2
	v_mad_i64_i32 v[42:43], s[2:3], v33, s74, v[36:37]
	v_or_b32_e32 v33, 6, v2
	v_mad_i64_i32 v[44:45], s[2:3], v33, s74, v[36:37]
	v_or_b32_e32 v33, 8, v2
	v_mad_i64_i32 v[46:47], s[2:3], v33, s74, v[36:37]
	v_or_b32_e32 v33, 10, v2
	v_mad_i64_i32 v[48:49], s[2:3], v33, s74, v[36:37]
	v_or_b32_e32 v33, 12, v2
	v_mad_i64_i32 v[50:51], s[2:3], v33, s74, v[36:37]
	v_or_b32_e32 v33, 14, v2
	v_mad_i64_i32 v[38:39], s[2:3], v2, s74, v[36:37]
	v_mad_i64_i32 v[52:53], s[2:3], v33, s74, v[36:37]
	global_load_dword v33, v[38:39], off
	global_load_dword v35, v[40:41], off
	global_load_dword v54, v[42:43], off
	global_load_dword v55, v[44:45], off
	global_load_dword v79, v[46:47], off
	global_load_dword v80, v[48:49], off
	global_load_dword v81, v[50:51], off
	global_load_dword v82, v[52:53], off
	v_or_b32_e32 v38, 16, v2
	v_or_b32_e32 v40, 18, v2
	v_or_b32_e32 v42, 20, v2
	v_or_b32_e32 v44, 22, v2
	v_or_b32_e32 v46, 24, v2
	v_or_b32_e32 v48, 26, v2
	v_or_b32_e32 v50, 28, v2
	v_or_b32_e32 v52, 30, v2
	v_mad_i64_i32 v[38:39], s[2:3], v38, s74, v[36:37]
	v_mad_i64_i32 v[40:41], s[2:3], v40, s74, v[36:37]
	v_mad_i64_i32 v[42:43], s[2:3], v42, s74, v[36:37]
	v_mad_i64_i32 v[44:45], s[2:3], v44, s74, v[36:37]
	v_mad_i64_i32 v[46:47], s[2:3], v46, s74, v[36:37]
	v_mad_i64_i32 v[48:49], s[2:3], v48, s74, v[36:37]
	v_mad_i64_i32 v[50:51], s[2:3], v50, s74, v[36:37]
	v_mad_i64_i32 v[52:53], s[2:3], v52, s74, v[36:37]
	global_load_dword v83, v[38:39], off
	global_load_dword v84, v[40:41], off
	global_load_dword v85, v[42:43], off
	global_load_dword v86, v[44:45], off
	global_load_dword v87, v[46:47], off
	global_load_dword v88, v[48:49], off
	global_load_dword v89, v[50:51], off
	global_load_dword v90, v[52:53], off
	v_or_b32_e32 v38, 32, v2
	v_or_b32_e32 v40, 34, v2
	v_or_b32_e32 v42, 36, v2
	v_or_b32_e32 v44, 38, v2
	v_or_b32_e32 v46, 40, v2
	v_or_b32_e32 v48, 42, v2
	v_or_b32_e32 v50, 44, v2
	v_or_b32_e32 v52, 46, v2
	v_mad_i64_i32 v[38:39], s[2:3], v38, s74, v[36:37]
	v_mad_i64_i32 v[40:41], s[2:3], v40, s74, v[36:37]
	v_mad_i64_i32 v[42:43], s[2:3], v42, s74, v[36:37]
	v_mad_i64_i32 v[44:45], s[2:3], v44, s74, v[36:37]
	v_mad_i64_i32 v[46:47], s[2:3], v46, s74, v[36:37]
	v_mad_i64_i32 v[48:49], s[2:3], v48, s74, v[36:37]
	v_mad_i64_i32 v[50:51], s[2:3], v50, s74, v[36:37]
	v_mad_i64_i32 v[52:53], s[2:3], v52, s74, v[36:37]
	global_load_dword v91, v[38:39], off
	global_load_dword v92, v[40:41], off
	global_load_dword v93, v[42:43], off
	global_load_dword v94, v[44:45], off
	global_load_dword v95, v[46:47], off
	global_load_dword v96, v[48:49], off
	global_load_dword v97, v[50:51], off
	s_nop 0
	global_load_dword v52, v[52:53], off
	v_or_b32_e32 v38, 48, v2
	v_or_b32_e32 v40, 50, v2
	v_or_b32_e32 v42, 52, v2
	v_or_b32_e32 v44, 54, v2
	v_or_b32_e32 v46, 56, v2
	v_or_b32_e32 v48, 58, v2
	v_or_b32_e32 v50, 60, v2
	v_or_b32_e32 v2, 62, v2
	v_mad_i64_i32 v[38:39], s[2:3], v38, s74, v[36:37]
	v_mad_i64_i32 v[40:41], s[2:3], v40, s74, v[36:37]
	v_mad_i64_i32 v[42:43], s[2:3], v42, s74, v[36:37]
	v_mad_i64_i32 v[44:45], s[2:3], v44, s74, v[36:37]
	v_mad_i64_i32 v[46:47], s[2:3], v46, s74, v[36:37]
	v_mad_i64_i32 v[48:49], s[2:3], v48, s74, v[36:37]
	v_mad_i64_i32 v[50:51], s[2:3], v50, s74, v[36:37]
	v_mad_i64_i32 v[36:37], s[2:3], v2, s74, v[36:37]
	global_load_dword v2, v[38:39], off
	s_nop 0
	global_load_dword v38, v[40:41], off
	global_load_dword v39, v[42:43], off
	s_nop 0
	global_load_dword v40, v[44:45], off
	global_load_dword v41, v[46:47], off
	global_load_dword v42, v[48:49], off
	global_load_dword v43, v[50:51], off
	s_nop 0
	global_load_dword v36, v[36:37], off
	s_waitcnt vmcnt(30)
	ds_write2_b32 v58, v33, v35 offset1:66
	s_waitcnt vmcnt(28)
	ds_write2_b32 v58, v54, v55 offset0:132 offset1:198
	v_add_u32_e32 v33, 0x400, v58
	s_waitcnt vmcnt(26)
	ds_write2_b32 v33, v79, v80 offset0:8 offset1:74
	s_waitcnt vmcnt(24)
	ds_write2_b32 v33, v81, v82 offset0:140 offset1:206
	v_add_u32_e32 v33, 0x800, v58
	s_waitcnt vmcnt(22)
	ds_write2_b32 v33, v83, v84 offset0:16 offset1:82
	s_waitcnt vmcnt(20)
	ds_write2_b32 v33, v85, v86 offset0:148 offset1:214
	v_add_u32_e32 v33, 0xc00, v58
	s_waitcnt vmcnt(18)
	ds_write2_b32 v33, v87, v88 offset0:24 offset1:90
	s_waitcnt vmcnt(16)
	ds_write2_b32 v33, v89, v90 offset0:156 offset1:222
	v_add_u32_e32 v33, 0x1000, v58
	s_waitcnt vmcnt(14)
	ds_write2_b32 v33, v91, v92 offset0:32 offset1:98
	s_waitcnt vmcnt(12)
	ds_write2_b32 v33, v93, v94 offset0:164 offset1:230
	v_add_u32_e32 v33, 0x1400, v58
	s_waitcnt vmcnt(10)
	ds_write2_b32 v33, v95, v96 offset0:40 offset1:106
	s_waitcnt vmcnt(8)
	ds_write2_b32 v33, v97, v52 offset0:172 offset1:238
	v_add_u32_e32 v33, 0x1800, v58
	s_waitcnt vmcnt(6)
	ds_write2_b32 v33, v2, v38 offset0:48 offset1:114
	s_waitcnt vmcnt(4)
	ds_write2_b32 v33, v39, v40 offset0:180 offset1:246
	v_add_u32_e32 v2, 0x1c00, v58
	s_waitcnt vmcnt(2)
	ds_write2_b32 v2, v41, v42 offset0:56 offset1:122
	s_waitcnt vmcnt(0)
	ds_write2_b32 v2, v43, v36 offset0:188 offset1:254
	s_waitcnt lgkmcnt(0)
	ds_read2_b32 v[36:37], v75 offset1:33
	s_waitcnt lgkmcnt(0)
	v_cvt_pk_bf16_f32 v36, v36, v37
	ds_read2_b32 v[38:39], v75 offset0:66 offset1:99
	s_waitcnt lgkmcnt(0)
	v_cvt_pk_bf16_f32 v37, v38, v39
	ds_read2_b32 v[38:39], v75 offset0:132 offset1:165
	s_waitcnt lgkmcnt(0)
	v_cvt_pk_bf16_f32 v38, v38, v39
	ds_read2_b32 v[40:41], v75 offset0:198 offset1:231
	v_add_u32_e32 v2, s10, v74
	s_waitcnt lgkmcnt(0)
	v_cvt_pk_bf16_f32 v39, v40, v41
	v_add_u32_e32 v40, 0xfffffc00, v2
	s_ashr_i32 s1, s0, 31
	v_ashrrev_i32_e32 v41, 31, v40
	v_lshl_add_u64 v[42:43], s[0:1], 1, v[30:31]
	v_lshlrev_b64 v[40:41], 12, v[40:41]
	v_lshl_add_u64 v[40:41], v[42:43], 0, v[40:41]
	ds_read2_b32 v[44:45], v75 offset0:8 offset1:41
	global_store_dwordx4 v[40:41], v[36:39], off sc1
	s_waitcnt lgkmcnt(0)
	s_nop 0
	v_cvt_pk_bf16_f32 v36, v44, v45
	ds_read2_b32 v[38:39], v75 offset0:74 offset1:107
	s_waitcnt lgkmcnt(0)
	v_cvt_pk_bf16_f32 v37, v38, v39
	ds_read2_b32 v[38:39], v75 offset0:140 offset1:173
	s_waitcnt lgkmcnt(0)
	v_cvt_pk_bf16_f32 v38, v38, v39
	ds_read2_b32 v[40:41], v75 offset0:206 offset1:239
	s_waitcnt lgkmcnt(0)
	v_cvt_pk_bf16_f32 v39, v40, v41
	v_add_u32_e32 v40, 0xfffffc08, v2
	v_ashrrev_i32_e32 v41, 31, v40
	v_lshlrev_b64 v[40:41], 12, v[40:41]
	v_lshl_add_u64 v[40:41], v[42:43], 0, v[40:41]
	ds_read2_b32 v[44:45], v75 offset0:16 offset1:49
	global_store_dwordx4 v[40:41], v[36:39], off sc1
	s_waitcnt lgkmcnt(0)
	s_nop 0
	v_cvt_pk_bf16_f32 v36, v44, v45
	ds_read2_b32 v[38:39], v75 offset0:82 offset1:115
	s_waitcnt lgkmcnt(0)
	v_cvt_pk_bf16_f32 v37, v38, v39
	ds_read2_b32 v[38:39], v75 offset0:148 offset1:181
	s_waitcnt lgkmcnt(0)
	v_cvt_pk_bf16_f32 v38, v38, v39
	ds_read2_b32 v[40:41], v75 offset0:214 offset1:247
	s_waitcnt lgkmcnt(0)
	v_cvt_pk_bf16_f32 v39, v40, v41
	v_add_u32_e32 v40, 0xfffffc10, v2
	v_ashrrev_i32_e32 v41, 31, v40
	v_lshlrev_b64 v[40:41], 12, v[40:41]
	v_lshl_add_u64 v[40:41], v[42:43], 0, v[40:41]
	ds_read2_b32 v[44:45], v75 offset0:24 offset1:57
	global_store_dwordx4 v[40:41], v[36:39], off sc1
	s_waitcnt lgkmcnt(0)
	s_nop 0
	v_cvt_pk_bf16_f32 v36, v44, v45
	ds_read2_b32 v[38:39], v75 offset0:90 offset1:123
	s_waitcnt lgkmcnt(0)
	v_cvt_pk_bf16_f32 v37, v38, v39
	ds_read2_b32 v[38:39], v75 offset0:156 offset1:189
	s_waitcnt lgkmcnt(0)
	v_cvt_pk_bf16_f32 v38, v38, v39
	ds_read2_b32 v[40:41], v75 offset0:222 offset1:255
	s_waitcnt lgkmcnt(0)
	v_cvt_pk_bf16_f32 v39, v40, v41
	v_add_u32_e32 v40, 0xfffffc18, v2
	v_ashrrev_i32_e32 v41, 31, v40
	v_lshlrev_b64 v[40:41], 12, v[40:41]
	v_lshl_add_u64 v[40:41], v[42:43], 0, v[40:41]
	global_store_dwordx4 v[40:41], v[36:39], off sc1
	s_waitcnt lgkmcnt(0)
	s_branch .LBB0_10

.LBB0_148:
	v_ashrrev_i32_e32 v16, 8, v1
	v_ashrrev_i32_e32 v17, 31, v16
	v_lshl_add_u64 v[16:17], v[16:17], 2, s[12:13]
	global_load_dwordx4 v[8:11], v[2:3], off
	global_load_dwordx4 v[12:15], v[2:3], off offset:-16
	v_add_u32_e32 v1, s4, v1
	global_load_dword v16, v[16:17], off
	v_cmp_lt_i32_e32 vcc, s2, v1
	v_lshl_add_u64 v[2:3], v[2:3], 0, s[6:7]
	s_or_b64 s[16:17], vcc, s[16:17]
	s_waitcnt vmcnt(0)
	v_mul_f32_e32 v11, v16, v11
	v_mul_f32_e32 v12, v16, v12
	v_mul_f32_e32 v13, v16, v13
	v_mul_f32_e32 v14, v16, v14
	v_mul_f32_e32 v15, v16, v15
	v_mul_f32_e32 v17, v16, v8
	v_mul_f32_e32 v18, v16, v9
	v_mul_f32_e32 v19, v16, v10
	v_cvt_pk_bf16_f32 v8, v12, v13
	v_cvt_pk_bf16_f32 v9, v14, v15
	v_cvt_pk_bf16_f32 v10, v17, v18
	v_cvt_pk_bf16_f32 v11, v19, v11
	global_store_dwordx4 v[4:5], v[8:11], off sc1
	v_lshl_add_u64 v[4:5], v[4:5], 0, s[8:9]
	s_andn2_b64 exec, exec, s[16:17]
	s_cbranch_execnz .LBB0_148

.LBB0_154:
	v_add_u32_e32 v6, s4, v6
	v_cmp_lt_i32_e32 vcc, s2, v6
	global_store_dwordx4 v[8:9], v[2:5], off sc1
	s_or_b64 s[8:9], vcc, s[8:9]
	v_lshl_add_u64 v[8:9], v[8:9], 0, s[6:7]
	s_andn2_b64 exec, exec, s[8:9]
	s_cbranch_execnz .LBB0_154

.LBB0_158:
	s_add_i32 s18, s20, s40
	s_cmpk_lt_i32 s18, 0x4000
	s_cselect_b64 s[22:23], -1, 0
	s_ashr_i32 s21, s20, 31
	s_lshl_b64 s[4:5], s[20:21], 11
	s_cmpk_gt_i32 s18, 0x3fff
	s_mov_b64 s[24:25], -1
	v_lshl_add_u64 v[22:23], s[4:5], 2, v[72:73]
	v_lshl_add_u64 v[90:91], s[4:5], 1, v[76:77]
	s_cbranch_scc0 .LBB0_161
	global_load_dwordx4 v[24:27], v[22:23], off
	global_load_dwordx4 v[28:31], v[22:23], off offset:1024
	global_load_dwordx4 v[32:35], v[22:23], off offset:2048
	global_load_dwordx4 v[18:21], v[22:23], off offset:3072
	v_add_co_u32_e32 v10, vcc, s2, v22
	s_nop 1
	v_addc_co_u32_e32 v11, vcc, 0, v23, vcc
	global_load_dwordx4 v[6:9], v[10:11], off
	global_load_dwordx4 v[14:17], v[10:11], off offset:1024
	global_load_dwordx4 v[2:5], v[10:11], off offset:3072
	s_nop 0
	global_load_dwordx4 v[10:13], v[10:11], off offset:2048
	v_cmp_lt_i32_e32 vcc, v69, v67
	global_load_dwordx4 v[36:39], v[74:75], off
	s_waitcnt vmcnt(8)
	v_mov_b32_e32 v42, v25
	v_cndmask_b32_e32 v40, v1, v69, vcc
	s_waitcnt vmcnt(7)
	v_mov_b32_e32 v43, v29
	v_mov_b32_e32 v46, v27
	v_mov_b32_e32 v47, v31
	v_lshlrev_b32_e32 v61, 2, v40
	v_mov_b32_e32 v40, v24
	v_mov_b32_e32 v41, v28
	v_mov_b32_e32 v44, v26
	v_mov_b32_e32 v45, v30
	s_waitcnt vmcnt(6)
	v_pk_mul_f32 v[48:49], v[34:35], v[34:35]
	v_pk_mul_f32 v[50:51], v[32:33], v[32:33]
	v_pk_mul_f32 v[42:43], v[42:43], v[42:43]
	v_pk_mul_f32 v[46:47], v[46:47], v[46:47]
	v_pk_mov_b32 v[56:57], v[50:51], v[48:49] op_sel:[1,0]
	v_mov_b32_e32 v51, v49
	v_pk_fma_f32 v[40:41], v[40:41], v[40:41], v[42:43]
	v_pk_fma_f32 v[42:43], v[44:45], v[44:45], v[46:47]
	s_waitcnt vmcnt(5)
	v_mul_f32_e32 v52, v19, v19
	v_mul_f32_e32 v54, v21, v21
	v_pk_add_f32 v[44:45], v[56:57], v[50:51]
	v_pk_add_f32 v[40:41], v[40:41], v[42:43]
	s_waitcnt vmcnt(4)
	v_mul_f32_e32 v63, v6, v6
	v_mul_f32_e32 v64, v7, v7
	v_mul_f32_e32 v65, v8, v8
	v_mul_f32_e32 v96, v9, v9
	v_pk_fma_f32 v[48:49], v[18:19], v[18:19], v[52:53] op_sel_hi:[1,1,0]
	v_pk_fma_f32 v[52:53], v[20:21], v[20:21], v[54:55] op_sel_hi:[1,1,0]
	v_pk_add_f32 v[42:43], v[44:45], v[44:45] op_sel:[0,1] op_sel_hi:[1,0]
	v_pk_add_f32 v[40:41], v[40:41], v[40:41] op_sel:[0,1] op_sel_hi:[1,0]
	s_waitcnt vmcnt(3)
	v_pk_mul_f32 v[54:55], v[16:17], v[16:17]
	v_pk_mul_f32 v[58:59], v[14:15], v[14:15]
	v_mov_b32_e32 v49, v65
	v_mov_b32_e32 v53, v96
	v_mov_b32_e32 v43, v64
	v_mov_b32_e32 v41, v63
	v_pk_mov_b32 v[46:47], v[58:59], v[54:55] op_sel:[1,0]
	v_mov_b32_e32 v59, v55
	v_pk_add_f32 v[44:45], v[48:49], v[52:53]
	v_pk_add_f32 v[40:41], v[40:41], v[42:43]
	s_waitcnt vmcnt(1)
	v_mul_f32_e32 v60, v11, v11
	v_mul_f32_e32 v62, v13, v13
	v_pk_add_f32 v[46:47], v[46:47], v[58:59]
	v_pk_add_f32 v[40:41], v[40:41], v[44:45]
	v_mul_f32_e32 v97, v2, v2
	v_mul_f32_e32 v98, v3, v3
	v_mul_f32_e32 v99, v4, v4
	v_mul_f32_e32 v100, v5, v5
	v_pk_fma_f32 v[50:51], v[10:11], v[10:11], v[60:61] op_sel_hi:[1,1,0]
	v_pk_fma_f32 v[54:55], v[12:13], v[12:13], v[62:63] op_sel_hi:[1,1,0]
	v_pk_add_f32 v[46:47], v[46:47], v[46:47] op_sel:[0,1] op_sel_hi:[1,0]
	v_pk_add_f32 v[40:41], v[40:41], v[40:41] op_sel:[0,1] op_sel_hi:[1,0]
	v_mov_b32_e32 v51, v99
	v_mov_b32_e32 v55, v100
	v_mov_b32_e32 v47, v98
	v_mov_b32_e32 v41, v97
	v_pk_add_f32 v[48:49], v[50:51], v[54:55]
	v_pk_add_f32 v[40:41], v[40:41], v[46:47]
	v_cmp_lt_i32_e32 vcc, v89, v67
	v_pk_add_f32 v[40:41], v[40:41], v[48:49]
	s_nop 0
	v_add_f32_e32 v40, v40, v41
	ds_bpermute_b32 v41, v61, v40
	v_cndmask_b32_e32 v42, v1, v89, vcc
	v_lshlrev_b32_e32 v42, 2, v42
	v_cmp_lt_i32_e32 vcc, v92, v67
	s_waitcnt lgkmcnt(0)
	v_add_f32_e32 v40, v40, v41
	ds_bpermute_b32 v41, v42, v40
	v_cndmask_b32_e32 v42, v1, v92, vcc
	v_lshlrev_b32_e32 v42, 2, v42
	v_cmp_lt_i32_e32 vcc, v93, v67
	s_waitcnt lgkmcnt(0)
	v_add_f32_e32 v40, v40, v41
	ds_bpermute_b32 v41, v42, v40
	v_cndmask_b32_e32 v42, v1, v93, vcc
	v_lshlrev_b32_e32 v42, 2, v42
	v_cmp_lt_i32_e32 vcc, v94, v67
	s_waitcnt lgkmcnt(0)
	v_add_f32_e32 v40, v40, v41
	ds_bpermute_b32 v41, v42, v40
	v_cndmask_b32_e32 v42, v1, v94, vcc
	v_lshlrev_b32_e32 v42, 2, v42
	v_cmp_lt_i32_e32 vcc, v95, v67
	s_waitcnt lgkmcnt(0)
	v_add_f32_e32 v40, v40, v41
	ds_bpermute_b32 v41, v42, v40
	v_cndmask_b32_e32 v42, v1, v95, vcc
	v_lshlrev_b32_e32 v42, 2, v42
	s_waitcnt lgkmcnt(0)
	v_add_f32_e32 v40, v40, v41
	ds_bpermute_b32 v41, v42, v40
	s_waitcnt lgkmcnt(0)
	v_add_f32_e32 v40, v40, v41
	v_fmamk_f32 v40, v40, 0x3a000000, v88
	v_mul_f32_e32 v41, 0x4b800000, v40
	v_cmp_gt_f32_e32 vcc, s3, v40
	s_nop 1
	v_cndmask_b32_e32 v40, v40, v41, vcc
	v_rsq_f32_e32 v40, v40
	s_nop 0
	v_mul_f32_e32 v41, 0x45800000, v40
	v_cndmask_b32_e32 v40, v40, v41, vcc
	v_mul_f32_e32 v24, v24, v40
	v_mul_f32_e32 v25, v25, v40
	v_mul_f32_e32 v26, v26, v40
	v_mul_f32_e32 v27, v27, v40
	s_waitcnt vmcnt(0)
	v_mul_f32_e32 v24, v36, v24
	v_mul_f32_e32 v25, v37, v25
	v_mul_f32_e32 v26, v38, v26
	v_mul_f32_e32 v27, v39, v27
	v_cvt_pk_bf16_f32 v24, v24, v25
	v_cvt_pk_bf16_f32 v25, v26, v27
	global_store_dwordx2 v[90:91], v[24:25], off sc1
	global_load_dwordx4 v[24:27], v[74:75], off offset:1024
	v_mul_f32_e32 v28, v28, v40
	v_mul_f32_e32 v29, v29, v40
	v_mul_f32_e32 v30, v30, v40
	v_mul_f32_e32 v31, v31, v40
	v_mul_f32_e32 v18, v18, v40
	v_mul_f32_e32 v19, v19, v40
	v_mul_f32_e32 v20, v20, v40
	v_mul_f32_e32 v21, v21, v40
	v_mul_f32_e32 v6, v6, v40
	v_mul_f32_e32 v7, v7, v40
	v_mul_f32_e32 v8, v8, v40
	v_mul_f32_e32 v9, v9, v40
	v_mul_f32_e32 v14, v14, v40
	v_mul_f32_e32 v15, v15, v40
	v_mul_f32_e32 v16, v16, v40
	v_mul_f32_e32 v17, v17, v40
	v_mul_f32_e32 v10, v10, v40
	v_mul_f32_e32 v11, v11, v40
	v_mul_f32_e32 v12, v12, v40
	v_mul_f32_e32 v13, v13, v40
	v_mul_f32_e32 v2, v2, v40
	v_mul_f32_e32 v3, v3, v40
	v_mul_f32_e32 v4, v4, v40
	v_mul_f32_e32 v5, v5, v40
	s_waitcnt vmcnt(0)
	v_mul_f32_e32 v24, v24, v28
	v_mul_f32_e32 v25, v25, v29
	v_mul_f32_e32 v26, v26, v30
	v_mul_f32_e32 v27, v27, v31
	v_cvt_pk_bf16_f32 v24, v24, v25
	v_cvt_pk_bf16_f32 v25, v26, v27
	global_store_dwordx2 v[90:91], v[24:25], off offset:512 sc1
	global_load_dwordx4 v[24:27], v[74:75], off offset:2048
	v_mul_f32_e32 v28, v32, v40
	v_mul_f32_e32 v29, v33, v40
	v_mul_f32_e32 v30, v34, v40
	v_mul_f32_e32 v31, v35, v40
	s_waitcnt vmcnt(0)
	v_mul_f32_e32 v24, v24, v28
	v_mul_f32_e32 v25, v25, v29
	v_mul_f32_e32 v26, v26, v30
	v_mul_f32_e32 v27, v27, v31
	v_cvt_pk_bf16_f32 v24, v24, v25
	v_cvt_pk_bf16_f32 v25, v26, v27
	global_store_dwordx2 v[90:91], v[24:25], off offset:1024 sc1
	global_load_dwordx4 v[24:27], v[74:75], off offset:3072
	s_waitcnt vmcnt(0)
	v_mul_f32_e32 v18, v18, v24
	v_mul_f32_e32 v19, v19, v25
	v_mul_f32_e32 v20, v20, v26
	v_mul_f32_e32 v21, v21, v27
	v_cvt_pk_bf16_f32 v18, v18, v19
	v_cvt_pk_bf16_f32 v19, v20, v21
	global_store_dwordx2 v[90:91], v[18:19], off offset:1536 sc1
	global_load_dwordx4 v[18:21], v[78:79], off
	s_waitcnt vmcnt(0)
	v_mul_f32_e32 v6, v6, v18
	v_mul_f32_e32 v7, v7, v19
	v_mul_f32_e32 v8, v8, v20
	v_mul_f32_e32 v9, v9, v21
	v_cvt_pk_bf16_f32 v6, v6, v7
	v_cvt_pk_bf16_f32 v7, v8, v9
	global_store_dwordx2 v[90:91], v[6:7], off offset:2048 sc1
	global_load_dwordx4 v[6:9], v[80:81], off
	s_waitcnt vmcnt(0)
	v_mul_f32_e32 v6, v14, v6
	v_mul_f32_e32 v7, v15, v7
	v_mul_f32_e32 v8, v16, v8
	v_mul_f32_e32 v9, v17, v9
	v_cvt_pk_bf16_f32 v6, v6, v7
	v_cvt_pk_bf16_f32 v7, v8, v9
	global_store_dwordx2 v[90:91], v[6:7], off offset:2560 sc1
	global_load_dwordx4 v[6:9], v[82:83], off
	s_waitcnt vmcnt(0)
	v_mul_f32_e32 v6, v10, v6
	v_mul_f32_e32 v7, v11, v7
	v_mul_f32_e32 v8, v12, v8
	v_mul_f32_e32 v9, v13, v9
	v_cvt_pk_bf16_f32 v6, v6, v7
	v_cvt_pk_bf16_f32 v7, v8, v9
	global_store_dwordx2 v[90:91], v[6:7], off offset:3072 sc1
	global_load_dwordx4 v[6:9], v[84:85], off
	s_waitcnt vmcnt(0)
	v_mul_f32_e32 v2, v2, v6
	v_mul_f32_e32 v3, v3, v7
	v_mul_f32_e32 v4, v4, v8
	v_mul_f32_e32 v5, v5, v9
	v_cvt_pk_bf16_f32 v2, v2, v3
	v_cvt_pk_bf16_f32 v3, v4, v5
	s_cbranch_execz .LBB0_162
.LBB0_160:
	v_lshl_add_u64 v[4:5], s[4:5], 1, v[76:77]
	global_store_dwordx2 v[4:5], v[2:3], off offset:3584 sc1
	s_and_saveexec_b64 s[4:5], s[0:1]
	s_cbranch_execz .LBB0_157
	s_branch .LBB0_163

.LBB0_162:
	s_ashr_i32 s19, s18, 31
	global_load_dwordx4 v[58:61], v[22:23], off
	global_load_dwordx4 v[50:53], v[22:23], off offset:1024
	global_load_dwordx4 v[42:45], v[22:23], off offset:2048
	global_load_dwordx4 v[34:37], v[22:23], off offset:3072
	v_add_co_u32_e32 v2, vcc, s2, v22
	s_lshl_b64 s[4:5], s[18:19], 13
	s_nop 0
	v_addc_co_u32_e32 v3, vcc, 0, v23, vcc
	v_lshl_add_u64 v[4:5], v[72:73], 0, s[4:5]
	global_load_dwordx4 v[30:33], v[2:3], off
	global_load_dwordx4 v[62:65], v[4:5], off
	global_load_dwordx4 v[54:57], v[4:5], off offset:1024
	global_load_dwordx4 v[46:49], v[4:5], off offset:2048
	v_add_co_u32_e32 v96, vcc, s2, v4
	s_waitcnt vmcnt(7)
	v_mov_b32_e32 v98, v59
	v_addc_co_u32_e32 v97, vcc, 0, v5, vcc
	global_load_dwordx4 v[26:29], v[96:97], off
	global_load_dwordx4 v[38:41], v[4:5], off offset:3072
	global_load_dwordx4 v[22:25], v[2:3], off offset:1024
	global_load_dwordx4 v[18:21], v[96:97], off offset:1024
	global_load_dwordx4 v[14:17], v[2:3], off offset:2048
	global_load_dwordx4 v[6:9], v[2:3], off offset:3072
	global_load_dwordx4 v[10:13], v[96:97], off offset:2048
	s_nop 0
	global_load_dwordx4 v[2:5], v[96:97], off offset:3072
	s_waitcnt vmcnt(14)
	v_mov_b32_e32 v99, v51
	v_mov_b32_e32 v102, v61
	v_mov_b32_e32 v103, v53
	v_mov_b32_e32 v96, v58
	v_mov_b32_e32 v97, v50
	v_mov_b32_e32 v100, v60
	v_mov_b32_e32 v101, v52
	s_waitcnt vmcnt(13)
	v_pk_mul_f32 v[104:105], v[44:45], v[44:45]
	v_pk_mul_f32 v[106:107], v[42:43], v[42:43]
	s_waitcnt vmcnt(12)
	v_mul_f32_e32 v108, v35, v35
	v_mul_f32_e32 v110, v37, v37
	v_pk_mul_f32 v[98:99], v[98:99], v[98:99]
	v_pk_mul_f32 v[102:103], v[102:103], v[102:103]
	v_pk_mov_b32 v[112:113], v[106:107], v[104:105] op_sel:[1,0]
	v_mov_b32_e32 v107, v105
	v_pk_fma_f32 v[104:105], v[34:35], v[34:35], v[108:109] op_sel_hi:[1,1,0]
	v_pk_fma_f32 v[108:109], v[36:37], v[36:37], v[110:111] op_sel_hi:[1,1,0]
	v_pk_fma_f32 v[96:97], v[96:97], v[96:97], v[98:99]
	v_pk_fma_f32 v[98:99], v[100:101], v[100:101], v[102:103]
	s_waitcnt vmcnt(10)
	v_mov_b32_e32 v102, v63
	s_waitcnt vmcnt(9)
	v_mov_b32_e32 v103, v55
	v_mov_b32_e32 v110, v65
	v_mov_b32_e32 v111, v57
	v_pk_add_f32 v[100:101], v[112:113], v[106:107]
	v_pk_add_f32 v[96:97], v[96:97], v[98:99]
	v_mov_b32_e32 v98, v62
	v_mov_b32_e32 v99, v54
	v_mov_b32_e32 v106, v64
	v_mov_b32_e32 v107, v56
	s_waitcnt vmcnt(8)
	v_pk_mul_f32 v[112:113], v[48:49], v[48:49]
	v_pk_mul_f32 v[114:115], v[46:47], v[46:47]
	v_pk_mul_f32 v[102:103], v[102:103], v[102:103]
	v_pk_mul_f32 v[110:111], v[110:111], v[110:111]
	v_mul_f32_e32 v118, v30, v30
	v_mul_f32_e32 v119, v31, v31
	v_pk_add_f32 v[100:101], v[100:101], v[100:101] op_sel:[0,1] op_sel_hi:[1,0]
	v_pk_mov_b32 v[116:117], v[114:115], v[112:113] op_sel:[1,0]
	v_mov_b32_e32 v115, v113
	v_pk_add_f32 v[96:97], v[96:97], v[96:97] op_sel:[0,1] op_sel_hi:[1,0]
	v_pk_fma_f32 v[98:99], v[98:99], v[98:99], v[102:103]
	v_pk_fma_f32 v[102:103], v[106:107], v[106:107], v[110:111]
	v_mul_f32_e32 v105, v32, v32
	v_mul_f32_e32 v109, v33, v33
	v_mov_b32_e32 v101, v119
	v_pk_add_f32 v[106:107], v[116:117], v[114:115]
	v_mov_b32_e32 v97, v118
	v_pk_add_f32 v[98:99], v[98:99], v[102:103]
	v_pk_add_f32 v[104:105], v[104:105], v[108:109]
	v_pk_add_f32 v[96:97], v[96:97], v[100:101]
	v_pk_add_f32 v[100:101], v[106:107], v[106:107] op_sel:[0,1] op_sel_hi:[1,0]
	v_pk_add_f32 v[98:99], v[98:99], v[98:99] op_sel:[0,1] op_sel_hi:[1,0]
	v_pk_add_f32 v[96:97], v[96:97], v[104:105]
	v_cmp_lt_i32_e32 vcc, v69, v67
	v_pk_add_f32 v[96:97], v[96:97], v[96:97] op_sel:[0,1] op_sel_hi:[1,0]
	s_waitcnt vmcnt(7)
	v_mul_f32_e32 v108, v26, v26
	v_mul_f32_e32 v109, v27, v27
	v_mov_b32_e32 v99, v108
	v_mov_b32_e32 v101, v109
	v_pk_add_f32 v[98:99], v[98:99], v[100:101]
	s_waitcnt vmcnt(6)
	v_mul_f32_e32 v100, v39, v39
	v_mul_f32_e32 v102, v41, v41
	v_mul_f32_e32 v110, v28, v28
	v_mul_f32_e32 v111, v29, v29
	v_pk_fma_f32 v[100:101], v[38:39], v[38:39], v[100:101] op_sel_hi:[1,1,0]
	v_pk_fma_f32 v[102:103], v[40:41], v[40:41], v[102:103] op_sel_hi:[1,1,0]
	v_mov_b32_e32 v101, v110
	v_mov_b32_e32 v103, v111
	v_pk_add_f32 v[100:101], v[100:101], v[102:103]
	s_waitcnt vmcnt(5)
	v_pk_mul_f32 v[102:103], v[22:23], v[22:23]
	v_pk_add_f32 v[100:101], v[98:99], v[100:101]
	v_pk_mul_f32 v[98:99], v[24:25], v[24:25]
	v_pk_add_f32 v[100:101], v[100:101], v[100:101] op_sel:[0,1] op_sel_hi:[1,0]
	v_pk_mov_b32 v[104:105], v[102:103], v[98:99] op_sel:[1,0]
	v_mov_b32_e32 v103, v99
	v_pk_add_f32 v[98:99], v[104:105], v[102:103]
	s_waitcnt vmcnt(4)
	v_pk_mul_f32 v[102:103], v[20:21], v[20:21]
	v_pk_mul_f32 v[104:105], v[18:19], v[18:19]
	v_pk_add_f32 v[98:99], v[98:99], v[98:99] op_sel:[0,1] op_sel_hi:[1,0]
	v_pk_mov_b32 v[106:107], v[104:105], v[102:103] op_sel:[1,0]
	v_mov_b32_e32 v105, v103
	v_pk_add_f32 v[102:103], v[106:107], v[104:105]
	s_waitcnt vmcnt(2)
	v_mul_f32_e32 v104, v6, v6
	v_mul_f32_e32 v105, v7, v7
	v_mov_b32_e32 v97, v104
	v_mov_b32_e32 v99, v105
	v_pk_add_f32 v[96:97], v[96:97], v[98:99]
	v_mul_f32_e32 v98, v15, v15
	v_mul_f32_e32 v104, v17, v17
	v_mul_f32_e32 v106, v8, v8
	v_mul_f32_e32 v107, v9, v9
	v_pk_fma_f32 v[98:99], v[14:15], v[14:15], v[98:99] op_sel_hi:[1,1,0]
	v_pk_fma_f32 v[104:105], v[16:17], v[16:17], v[104:105] op_sel_hi:[1,1,0]
	v_mov_b32_e32 v99, v106
	v_mov_b32_e32 v105, v107
	v_pk_add_f32 v[98:99], v[98:99], v[104:105]
	s_waitcnt vmcnt(0)
	v_mul_f32_e32 v106, v2, v2
	v_pk_add_f32 v[104:105], v[96:97], v[98:99]
	global_load_dwordx4 v[96:99], v[74:75], off
	v_mul_f32_e32 v107, v3, v3
	v_pk_add_f32 v[102:103], v[102:103], v[102:103] op_sel:[0,1] op_sel_hi:[1,0]
	v_mov_b32_e32 v101, v106
	v_mov_b32_e32 v103, v107
	v_pk_add_f32 v[100:101], v[100:101], v[102:103]
	v_mul_f32_e32 v102, v11, v11
	v_mul_f32_e32 v106, v13, v13
	v_mul_f32_e32 v108, v4, v4
	v_mul_f32_e32 v109, v5, v5
	v_pk_fma_f32 v[102:103], v[10:11], v[10:11], v[102:103] op_sel_hi:[1,1,0]
	v_pk_fma_f32 v[106:107], v[12:13], v[12:13], v[106:107] op_sel_hi:[1,1,0]
	v_mov_b32_e32 v103, v108
	v_mov_b32_e32 v107, v109
	v_pk_add_f32 v[102:103], v[102:103], v[106:107]
	s_nop 0
	v_pk_add_f32 v[100:101], v[100:101], v[102:103]
	v_cndmask_b32_e32 v102, v1, v69, vcc
	v_lshlrev_b32_e32 v106, 2, v102
	v_mov_b32_e32 v102, v100
	v_mov_b32_e32 v103, v104
	v_mov_b32_e32 v104, v101
	v_pk_add_f32 v[100:101], v[102:103], v[104:105]
	ds_bpermute_b32 v103, v106, v101
	ds_bpermute_b32 v102, v106, v100
	v_cmp_lt_i32_e32 vcc, v89, v67
	s_waitcnt lgkmcnt(0)
	v_pk_add_f32 v[100:101], v[100:101], v[102:103]
	v_cndmask_b32_e32 v104, v1, v89, vcc
	v_lshlrev_b32_e32 v104, 2, v104
	ds_bpermute_b32 v103, v104, v101
	ds_bpermute_b32 v102, v104, v100
	v_cmp_lt_i32_e32 vcc, v92, v67
	s_waitcnt lgkmcnt(0)
	v_pk_add_f32 v[100:101], v[100:101], v[102:103]
	v_cndmask_b32_e32 v104, v1, v92, vcc
	v_lshlrev_b32_e32 v104, 2, v104
	ds_bpermute_b32 v103, v104, v101
	ds_bpermute_b32 v102, v104, v100
	v_cmp_lt_i32_e32 vcc, v93, v67
	s_waitcnt lgkmcnt(0)
	v_pk_add_f32 v[100:101], v[100:101], v[102:103]
	v_cndmask_b32_e32 v104, v1, v93, vcc
	v_lshlrev_b32_e32 v104, 2, v104
	ds_bpermute_b32 v103, v104, v101
	ds_bpermute_b32 v102, v104, v100
	v_cmp_lt_i32_e32 vcc, v94, v67
	s_waitcnt lgkmcnt(0)
	v_pk_add_f32 v[100:101], v[100:101], v[102:103]
	v_cndmask_b32_e32 v104, v1, v94, vcc
	v_lshlrev_b32_e32 v104, 2, v104
	ds_bpermute_b32 v103, v104, v101
	ds_bpermute_b32 v102, v104, v100
	v_cmp_lt_i32_e32 vcc, v95, v67
	s_waitcnt lgkmcnt(0)
	v_pk_add_f32 v[100:101], v[100:101], v[102:103]
	v_cndmask_b32_e32 v104, v1, v95, vcc
	v_lshlrev_b32_e32 v104, 2, v104
	ds_bpermute_b32 v103, v104, v101
	ds_bpermute_b32 v102, v104, v100
	s_waitcnt lgkmcnt(0)
	v_pk_add_f32 v[100:101], v[100:101], v[102:103]
	s_nop 0
	v_pk_fma_f32 v[100:101], v[100:101], s[6:7], v[88:89] op_sel_hi:[1,0,0]
	s_nop 0
	v_mul_f32_e32 v102, 0x4b800000, v101
	v_cmp_gt_f32_e32 vcc, s3, v101
	v_cmp_gt_f32_e64 s[4:5], s3, v100
	s_nop 0
	v_cndmask_b32_e32 v101, v101, v102, vcc
	v_rsq_f32_e32 v101, v101
	v_mul_f32_e32 v102, 0x4b800000, v100
	v_cndmask_b32_e64 v100, v100, v102, s[4:5]
	v_rsq_f32_e32 v100, v100
	v_mul_f32_e32 v102, 0x45800000, v101
	v_cndmask_b32_e32 v102, v101, v102, vcc
	v_mul_f32_e32 v58, v58, v102
	v_mul_f32_e32 v59, v59, v102
	s_waitcnt vmcnt(0)
	v_mul_f32_e32 v58, v96, v58
	v_mul_f32_e32 v59, v97, v59
	v_cvt_pk_bf16_f32 v58, v58, v59
	v_mul_f32_e32 v59, v60, v102
	v_mul_f32_e32 v101, 0x45800000, v100
	v_mul_f32_e32 v59, v98, v59
	v_mul_f32_e32 v60, v61, v102
	v_cndmask_b32_e64 v103, v100, v101, s[4:5]
	v_mul_f32_e32 v60, v99, v60
	v_cvt_pk_bf16_f32 v59, v59, v60
	global_store_dwordx2 v[90:91], v[58:59], off sc1
	v_mul_f32_e32 v58, v62, v103
	v_mul_f32_e32 v59, v63, v103
	v_mul_f32_e32 v58, v96, v58
	v_mul_f32_e32 v59, v97, v59
	s_lshl_b64 s[4:5], s[18:19], 12
	v_cvt_pk_bf16_f32 v58, v58, v59
	v_mul_f32_e32 v59, v64, v103
	v_lshl_add_u64 v[100:101], v[76:77], 0, s[4:5]
	v_mul_f32_e32 v59, v98, v59
	v_mul_f32_e32 v60, v65, v103
	v_mul_f32_e32 v60, v99, v60
	v_cvt_pk_bf16_f32 v59, v59, v60
	global_store_dwordx2 v[100:101], v[58:59], off sc1
	global_load_dwordx4 v[58:61], v[74:75], off offset:1024
	v_mul_f32_e32 v50, v50, v102
	v_mul_f32_e32 v51, v51, v102
	v_mul_f32_e32 v52, v52, v102
	v_mul_f32_e32 v42, v42, v102
	v_mul_f32_e32 v43, v43, v102
	v_mul_f32_e32 v44, v44, v102
	v_mul_f32_e32 v45, v45, v102
	v_mul_f32_e32 v46, v46, v103
	v_mul_f32_e32 v47, v47, v103
	v_mul_f32_e32 v48, v48, v103
	v_mul_f32_e32 v49, v49, v103
	v_mul_f32_e32 v34, v34, v102
	v_mul_f32_e32 v35, v35, v102
	v_mul_f32_e32 v36, v36, v102
	v_mul_f32_e32 v37, v37, v102
	v_mul_f32_e32 v38, v38, v103
	v_mul_f32_e32 v39, v39, v103
	v_mul_f32_e32 v40, v40, v103
	v_mul_f32_e32 v41, v41, v103
	v_mul_f32_e32 v30, v30, v102
	v_mul_f32_e32 v31, v31, v102
	v_mul_f32_e32 v32, v32, v102
	v_mul_f32_e32 v33, v33, v102
	v_mul_f32_e32 v26, v26, v103
	v_mul_f32_e32 v27, v27, v103
	v_mul_f32_e32 v28, v28, v103
	v_mul_f32_e32 v29, v29, v103
	v_mul_f32_e32 v22, v22, v102
	v_mul_f32_e32 v23, v23, v102
	v_mul_f32_e32 v24, v24, v102
	v_mul_f32_e32 v25, v25, v102
	v_mul_f32_e32 v18, v18, v103
	v_mul_f32_e32 v19, v19, v103
	v_mul_f32_e32 v20, v20, v103
	v_mul_f32_e32 v21, v21, v103
	v_mul_f32_e32 v14, v14, v102
	v_mul_f32_e32 v15, v15, v102
	v_mul_f32_e32 v16, v16, v102
	v_mul_f32_e32 v17, v17, v102
	v_mul_f32_e32 v10, v10, v103
	v_mul_f32_e32 v11, v11, v103
	v_mul_f32_e32 v12, v12, v103
	v_mul_f32_e32 v13, v13, v103
	v_mul_f32_e32 v6, v6, v102
	v_mul_f32_e32 v7, v7, v102
	v_mul_f32_e32 v8, v8, v102
	v_mul_f32_e32 v9, v9, v102
	v_mul_f32_e32 v2, v2, v103
	v_mul_f32_e32 v3, v3, v103
	s_lshl_b64 s[4:5], s[18:19], 11
	v_mul_f32_e32 v4, v4, v103
	v_mul_f32_e32 v5, v5, v103
	s_waitcnt vmcnt(0)
	v_mul_f32_e32 v50, v50, v58
	v_mul_f32_e32 v51, v51, v59
	v_cvt_pk_bf16_f32 v50, v50, v51
	v_mul_f32_e32 v51, v53, v102
	v_mul_f32_e32 v51, v51, v61
	v_mul_f32_e32 v52, v52, v60
	v_cvt_pk_bf16_f32 v51, v52, v51
	global_store_dwordx2 v[90:91], v[50:51], off offset:512 sc1
	v_mul_f32_e32 v50, v54, v103
	v_mul_f32_e32 v51, v55, v103
	v_mul_f32_e32 v50, v58, v50
	v_mul_f32_e32 v51, v59, v51
	v_cvt_pk_bf16_f32 v50, v50, v51
	v_mul_f32_e32 v51, v56, v103
	v_mul_f32_e32 v51, v60, v51
	v_mul_f32_e32 v52, v57, v103
	v_mul_f32_e32 v52, v61, v52
	v_cvt_pk_bf16_f32 v51, v51, v52
	global_store_dwordx2 v[100:101], v[50:51], off offset:512 sc1
	global_load_dwordx4 v[50:53], v[74:75], off offset:2048
	s_waitcnt vmcnt(0)
	v_mul_f32_e32 v42, v42, v50
	v_mul_f32_e32 v43, v43, v51
	v_mul_f32_e32 v44, v44, v52
	v_mul_f32_e32 v45, v45, v53
	v_cvt_pk_bf16_f32 v42, v42, v43
	v_cvt_pk_bf16_f32 v43, v44, v45
	v_mul_f32_e32 v46, v46, v50
	v_mul_f32_e32 v47, v47, v51
	v_mul_f32_e32 v48, v48, v52
	v_mul_f32_e32 v49, v49, v53
	global_store_dwordx2 v[90:91], v[42:43], off offset:1024 sc1
	v_cvt_pk_bf16_f32 v42, v46, v47
	v_cvt_pk_bf16_f32 v43, v48, v49
	global_store_dwordx2 v[100:101], v[42:43], off offset:1024 sc1
	global_load_dwordx4 v[42:45], v[74:75], off offset:3072
	s_waitcnt vmcnt(0)
	v_mul_f32_e32 v34, v34, v42
	v_mul_f32_e32 v35, v35, v43
	v_mul_f32_e32 v36, v36, v44
	v_mul_f32_e32 v37, v37, v45
	v_cvt_pk_bf16_f32 v34, v34, v35
	v_cvt_pk_bf16_f32 v35, v36, v37
	v_mul_f32_e32 v38, v38, v42
	v_mul_f32_e32 v39, v39, v43
	v_mul_f32_e32 v40, v40, v44
	v_mul_f32_e32 v41, v41, v45
	global_store_dwordx2 v[90:91], v[34:35], off offset:1536 sc1
	v_cvt_pk_bf16_f32 v34, v38, v39
	v_cvt_pk_bf16_f32 v35, v40, v41
	global_store_dwordx2 v[100:101], v[34:35], off offset:1536 sc1
	global_load_dwordx4 v[34:37], v[78:79], off
	s_waitcnt vmcnt(0)
	v_mul_f32_e32 v30, v30, v34
	v_mul_f32_e32 v31, v31, v35
	v_mul_f32_e32 v32, v32, v36
	v_mul_f32_e32 v33, v33, v37
	v_mul_f32_e32 v34, v26, v34
	v_mul_f32_e32 v35, v27, v35
	v_cvt_pk_bf16_f32 v26, v30, v31
	v_cvt_pk_bf16_f32 v27, v32, v33
	v_mul_f32_e32 v28, v28, v36
	v_mul_f32_e32 v29, v29, v37
	global_store_dwordx2 v[90:91], v[26:27], off offset:2048 sc1
	v_cvt_pk_bf16_f32 v26, v34, v35
	v_cvt_pk_bf16_f32 v27, v28, v29
	global_store_dwordx2 v[100:101], v[26:27], off offset:2048 sc1
	global_load_dwordx4 v[26:29], v[80:81], off
	s_waitcnt vmcnt(0)
	v_mul_f32_e32 v22, v22, v26
	v_mul_f32_e32 v23, v23, v27
	v_mul_f32_e32 v24, v24, v28
	v_mul_f32_e32 v25, v25, v29
	v_mul_f32_e32 v26, v18, v26
	v_mul_f32_e32 v27, v19, v27
	v_cvt_pk_bf16_f32 v18, v22, v23
	v_cvt_pk_bf16_f32 v19, v24, v25
	v_mul_f32_e32 v20, v20, v28
	v_mul_f32_e32 v21, v21, v29
	global_store_dwordx2 v[90:91], v[18:19], off offset:2560 sc1
	v_cvt_pk_bf16_f32 v18, v26, v27
	v_cvt_pk_bf16_f32 v19, v20, v21
	global_store_dwordx2 v[100:101], v[18:19], off offset:2560 sc1
	global_load_dwordx4 v[18:21], v[82:83], off
	s_waitcnt vmcnt(0)
	v_mul_f32_e32 v14, v14, v18
	v_mul_f32_e32 v15, v15, v19
	v_mul_f32_e32 v16, v16, v20
	v_mul_f32_e32 v17, v17, v21
	v_mul_f32_e32 v18, v10, v18
	v_mul_f32_e32 v19, v11, v19
	v_cvt_pk_bf16_f32 v10, v14, v15
	v_cvt_pk_bf16_f32 v11, v16, v17
	v_mul_f32_e32 v12, v12, v20
	v_mul_f32_e32 v13, v13, v21
	global_store_dwordx2 v[90:91], v[10:11], off offset:3072 sc1
	v_cvt_pk_bf16_f32 v10, v18, v19
	v_cvt_pk_bf16_f32 v11, v12, v13
	global_store_dwordx2 v[100:101], v[10:11], off offset:3072 sc1
	global_load_dwordx4 v[10:13], v[84:85], off
	s_waitcnt vmcnt(0)
	v_mul_f32_e32 v6, v6, v10
	v_mul_f32_e32 v7, v7, v11
	v_mul_f32_e32 v8, v8, v12
	v_mul_f32_e32 v9, v9, v13
	v_mul_f32_e32 v10, v2, v10
	v_mul_f32_e32 v11, v3, v11
	v_cvt_pk_bf16_f32 v2, v6, v7
	v_cvt_pk_bf16_f32 v3, v8, v9
	v_mul_f32_e32 v4, v4, v12
	v_mul_f32_e32 v5, v5, v13
	global_store_dwordx2 v[90:91], v[2:3], off offset:3584 sc1
	v_cvt_pk_bf16_f32 v2, v10, v11
	v_cvt_pk_bf16_f32 v3, v4, v5
	v_lshl_add_u64 v[4:5], s[4:5], 1, v[76:77]
	global_store_dwordx2 v[4:5], v[2:3], off offset:3584 sc1
	s_and_saveexec_b64 s[4:5], s[0:1]
	s_cbranch_execz .LBB0_157

.LBB0_167:
	global_load_dwordx4 v[26:29], v[16:17], off offset:-3072
	global_load_dwordx4 v[30:33], v[16:17], off offset:-2048
	global_load_dwordx4 v[2:5], v[16:17], off
	global_load_dwordx4 v[34:37], v[16:17], off offset:-1024
	v_add_co_u32_e32 v50, vcc, 0xfffff000, v16
	global_load_dwordx4 v[38:41], v[6:7], off
	s_nop 0
	v_addc_co_u32_e32 v51, vcc, -1, v17, vcc
	global_load_dwordx4 v[42:45], v[50:51], off offset:-3072
	global_load_dwordx4 v[46:49], v[50:51], off offset:-2048
	s_nop 0
	global_load_dwordx4 v[50:53], v[50:51], off offset:-1024
	s_nop 0
	global_load_dwordx4 v[54:57], v[16:17], off offset:-4096
	s_add_i32 s66, s66, s40
	s_cmpk_gt_i32 s66, 0x3ff
	v_lshl_add_u64 v[16:17], v[16:17], 0, s[0:1]
	s_waitcnt vmcnt(8)
	v_mul_f32_e32 v81, v26, v26
	s_waitcnt vmcnt(7)
	v_pk_mul_f32 v[58:59], v[32:33], v[32:33]
	v_pk_mul_f32 v[60:61], v[30:31], v[30:31]
	s_waitcnt vmcnt(5)
	v_mul_f32_e32 v62, v35, v35
	v_mul_f32_e32 v64, v37, v37
	v_mul_f32_e32 v79, v4, v4
	v_mul_f32_e32 v87, v5, v5
	v_pk_mov_b32 v[66:67], v[60:61], v[58:59] op_sel:[1,0]
	v_mov_b32_e32 v61, v59
	v_pk_fma_f32 v[58:59], v[34:35], v[34:35], v[62:63] op_sel_hi:[1,1,0]
	v_pk_fma_f32 v[62:63], v[36:37], v[36:37], v[64:65] op_sel_hi:[1,1,0]
	s_waitcnt vmcnt(3)
	v_mov_b32_e32 v68, v43
	s_waitcnt vmcnt(2)
	v_mov_b32_e32 v69, v47
	v_mov_b32_e32 v72, v45
	v_mov_b32_e32 v73, v49
	v_mov_b32_e32 v64, v42
	v_mov_b32_e32 v65, v46
	v_mov_b32_e32 v70, v44
	v_mov_b32_e32 v71, v48
	s_waitcnt vmcnt(1)
	v_pk_mul_f32 v[74:75], v[52:53], v[52:53]
	v_pk_mul_f32 v[76:77], v[50:51], v[50:51]
	v_pk_add_f32 v[60:61], v[66:67], v[60:61]
	v_mov_b32_e32 v59, v79
	v_mov_b32_e32 v63, v87
	v_pk_mul_f32 v[66:67], v[68:69], v[68:69]
	v_pk_mul_f32 v[68:69], v[72:73], v[72:73]
	v_pk_mov_b32 v[72:73], v[76:77], v[74:75] op_sel:[1,0]
	v_mov_b32_e32 v77, v75
	v_pk_add_f32 v[58:59], v[58:59], v[62:63]
	v_pk_fma_f32 v[62:63], v[64:65], v[64:65], v[66:67]
	v_pk_fma_f32 v[64:65], v[70:71], v[70:71], v[68:69]
	s_waitcnt vmcnt(0)
	v_mul_f32_e32 v78, v55, v55
	v_mul_f32_e32 v80, v57, v57
	v_pk_add_f32 v[66:67], v[72:73], v[76:77]
	v_pk_add_f32 v[62:63], v[62:63], v[64:65]
	v_mul_f32_e32 v82, v27, v27
	v_mul_f32_e32 v83, v28, v28
	v_mul_f32_e32 v84, v29, v29
	v_pk_fma_f32 v[74:75], v[54:55], v[54:55], v[78:79] op_sel_hi:[1,1,0]
	v_pk_fma_f32 v[78:79], v[56:57], v[56:57], v[80:81] op_sel_hi:[1,1,0]
	v_pk_add_f32 v[64:65], v[66:67], v[66:67] op_sel:[0,1] op_sel_hi:[1,0]
	v_pk_add_f32 v[62:63], v[62:63], v[62:63] op_sel:[0,1] op_sel_hi:[1,0]
	v_mov_b32_e32 v75, v83
	v_mov_b32_e32 v79, v84
	v_mov_b32_e32 v65, v82
	v_mov_b32_e32 v63, v81
	v_pk_add_f32 v[66:67], v[74:75], v[78:79]
	v_pk_add_f32 v[62:63], v[62:63], v[64:65]
	v_mul_f32_e32 v85, v2, v2
	v_pk_add_f32 v[62:63], v[62:63], v[66:67]
	v_mul_f32_e32 v86, v3, v3
	v_pk_add_f32 v[60:61], v[60:61], v[60:61] op_sel:[0,1] op_sel_hi:[1,0]
	v_pk_add_f32 v[62:63], v[62:63], v[62:63] op_sel:[0,1] op_sel_hi:[1,0]
	v_mov_b32_e32 v61, v86
	v_mov_b32_e32 v63, v85
	v_pk_add_f32 v[60:61], v[62:63], v[60:61]
	s_nop 0
	v_pk_add_f32 v[58:59], v[60:61], v[58:59]
	s_nop 0
	v_add_f32_e32 v58, v58, v59
	ds_bpermute_b32 v59, v1, v58
	s_waitcnt lgkmcnt(0)
	v_add_f32_e32 v58, v58, v59
	ds_bpermute_b32 v59, v20, v58
	s_waitcnt lgkmcnt(0)
	v_add_f32_e32 v58, v58, v59
	ds_bpermute_b32 v59, v21, v58
	s_waitcnt lgkmcnt(0)
	v_add_f32_e32 v58, v58, v59
	ds_bpermute_b32 v59, v22, v58
	s_waitcnt lgkmcnt(0)
	v_add_f32_e32 v58, v58, v59
	ds_bpermute_b32 v59, v23, v58
	s_waitcnt lgkmcnt(0)
	v_add_f32_e32 v58, v58, v59
	ds_bpermute_b32 v59, v24, v58
	s_waitcnt lgkmcnt(0)
	v_add_f32_e32 v58, v58, v59
	v_fmamk_f32 v58, v58, 0x3a000000, v25
	v_mul_f32_e32 v59, 0x4b800000, v58
	v_cmp_gt_f32_e32 vcc, s3, v58
	s_nop 1
	v_cndmask_b32_e32 v58, v58, v59, vcc
	v_rsq_f32_e32 v58, v58
	s_nop 0
	v_mul_f32_e32 v59, 0x45800000, v58
	v_cndmask_b32_e32 v58, v58, v59, vcc
	v_mul_f32_e32 v42, v42, v58
	v_mul_f32_e32 v43, v43, v58
	v_mul_f32_e32 v44, v44, v58
	v_mul_f32_e32 v45, v45, v58
	v_mul_f32_e32 v38, v38, v42
	v_mul_f32_e32 v39, v39, v43
	v_mul_f32_e32 v40, v40, v44
	v_mul_f32_e32 v41, v41, v45
	v_cvt_pk_bf16_f32 v38, v38, v39
	v_cvt_pk_bf16_f32 v39, v40, v41
	global_store_dwordx2 v[18:19], v[38:39], off offset:-2048 sc1
	global_load_dwordx4 v[38:41], v[6:7], off offset:1024
	v_mul_f32_e32 v42, v46, v58
	v_mul_f32_e32 v43, v47, v58
	v_mul_f32_e32 v44, v48, v58
	v_mul_f32_e32 v45, v49, v58
	v_mul_f32_e32 v26, v26, v58
	v_mul_f32_e32 v27, v27, v58
	v_mul_f32_e32 v28, v28, v58
	v_mul_f32_e32 v29, v29, v58
	v_mul_f32_e32 v30, v30, v58
	v_mul_f32_e32 v31, v31, v58
	v_mul_f32_e32 v32, v32, v58
	v_mul_f32_e32 v33, v33, v58
	v_mul_f32_e32 v2, v2, v58
	v_mul_f32_e32 v3, v3, v58
	v_mul_f32_e32 v4, v4, v58
	v_mul_f32_e32 v5, v5, v58
	s_waitcnt vmcnt(0)
	v_mul_f32_e32 v38, v38, v42
	v_mul_f32_e32 v39, v39, v43
	v_mul_f32_e32 v40, v40, v44
	v_mul_f32_e32 v41, v41, v45
	v_cvt_pk_bf16_f32 v38, v38, v39
	v_cvt_pk_bf16_f32 v39, v40, v41
	global_store_dwordx2 v[18:19], v[38:39], off offset:-1536 sc1
	global_load_dwordx4 v[38:41], v[6:7], off offset:2048
	v_mul_f32_e32 v42, v50, v58
	v_mul_f32_e32 v43, v51, v58
	v_mul_f32_e32 v44, v52, v58
	v_mul_f32_e32 v45, v53, v58
	s_waitcnt vmcnt(0)
	v_mul_f32_e32 v38, v38, v42
	v_mul_f32_e32 v39, v39, v43
	v_mul_f32_e32 v40, v40, v44
	v_mul_f32_e32 v41, v41, v45
	v_cvt_pk_bf16_f32 v38, v38, v39
	v_cvt_pk_bf16_f32 v39, v40, v41
	global_store_dwordx2 v[18:19], v[38:39], off offset:-1024 sc1
	global_load_dwordx4 v[38:41], v[6:7], off offset:3072
	v_mul_f32_e32 v42, v54, v58
	v_mul_f32_e32 v43, v55, v58
	v_mul_f32_e32 v44, v56, v58
	v_mul_f32_e32 v45, v57, v58
	s_waitcnt vmcnt(0)
	v_mul_f32_e32 v38, v42, v38
	v_mul_f32_e32 v39, v43, v39
	v_mul_f32_e32 v40, v44, v40
	v_mul_f32_e32 v41, v45, v41
	v_cvt_pk_bf16_f32 v38, v38, v39
	v_cvt_pk_bf16_f32 v39, v40, v41
	global_store_dwordx2 v[18:19], v[38:39], off offset:-512 sc1
	global_load_dwordx4 v[38:41], v[8:9], off
	s_waitcnt vmcnt(0)
	v_mul_f32_e32 v26, v26, v38
	v_mul_f32_e32 v27, v27, v39
	v_mul_f32_e32 v28, v28, v40
	v_mul_f32_e32 v29, v29, v41
	v_cvt_pk_bf16_f32 v26, v26, v27
	v_cvt_pk_bf16_f32 v27, v28, v29
	global_store_dwordx2 v[18:19], v[26:27], off sc1
	global_load_dwordx4 v[26:29], v[10:11], off
	s_waitcnt vmcnt(0)
	v_mul_f32_e32 v26, v30, v26
	v_mul_f32_e32 v27, v31, v27
	v_mul_f32_e32 v28, v32, v28
	v_mul_f32_e32 v29, v33, v29
	v_cvt_pk_bf16_f32 v26, v26, v27
	v_cvt_pk_bf16_f32 v27, v28, v29
	global_store_dwordx2 v[18:19], v[26:27], off offset:512 sc1
	global_load_dwordx4 v[26:29], v[12:13], off
	v_mul_f32_e32 v30, v34, v58
	v_mul_f32_e32 v31, v35, v58
	v_mul_f32_e32 v32, v36, v58
	v_mul_f32_e32 v33, v37, v58
	s_waitcnt vmcnt(0)
	v_mul_f32_e32 v26, v30, v26
	v_mul_f32_e32 v27, v31, v27
	v_mul_f32_e32 v28, v32, v28
	v_mul_f32_e32 v29, v33, v29
	v_cvt_pk_bf16_f32 v26, v26, v27
	v_cvt_pk_bf16_f32 v27, v28, v29
	global_store_dwordx2 v[18:19], v[26:27], off offset:1024 sc1
	global_load_dwordx4 v[26:29], v[14:15], off
	s_waitcnt vmcnt(0)
	v_mul_f32_e32 v2, v2, v26
	v_mul_f32_e32 v3, v3, v27
	v_mul_f32_e32 v4, v4, v28
	v_mul_f32_e32 v5, v5, v29
	v_cvt_pk_bf16_f32 v2, v2, v3
	v_cvt_pk_bf16_f32 v3, v4, v5
	global_store_dwordx2 v[18:19], v[2:3], off offset:1536 sc1
	v_lshl_add_u64 v[18:19], v[18:19], 0, s[4:5]
	s_cbranch_scc0 .LBB0_167
